# v12 + MMA segment trim: s_setprio 1 moved before the phase barrier, redundant post-barrier lgkmcnt wait and mid-run setprio flip removed (all GEMM loops, placement preserved)
# speedup vs baseline: 1.0089x; 1.0089x over previous
; #define PG8_STAGE(bufoff, gbase, voff) do { _Pragma("unroll") for (int _i = 0; _i < 2; ++_i) \
;         __builtin_amdgcn_global_load_lds((const unsigned*)((const char*)(gbase) + (voff)[_i]), (LAS unsigned*)(lds + (bufoff) + ldsw + _i * 8192), 16, 0, 0); } while (0)
; #define PG8_LDA(dst, b, h) do { _Pragma("unroll") for (int m = 0; m < 4; ++m) _Pragma("unroll") for (int k = 0; k < 2; ++k) dst[m][k] = *(const LAS bf16x8*)(lds + PG8_SA(b, h) + aoff + m * 2048 + k * 1024); } while (0)
; #define PG8_LDB(dst, b, h) do { _Pragma("unroll") for (int n = 0; n < 2; ++n) _Pragma("unroll") for (int k = 0; k < 2; ++k) dst[n][k] = *(const LAS bf16x8*)(lds + PG8_SB(b, h) + boff + n * 2048 + k * 1024); } while (0)
; #define PG8_MMA(ai, bj, At, Bt) do { __builtin_amdgcn_s_setprio(1); _Pragma("unroll") for (int m = 0; m < 4; ++m) _Pragma("unroll") for (int n = 0; n < 2; ++n) _Pragma("unroll") for (int k = 0; k < 2; ++k) \
;         acc[ai][bj][m][n] = __builtin_amdgcn_mfma_f32_16x16x32_bf16(Bt[n][k], At[m][k], acc[ai][bj][m][n], 0, 0, 0); __builtin_amdgcn_s_setprio(0); } while (0)
; #define PG8_WAIT_V(n) asm volatile("s_waitcnt vmcnt(" #n ")" ::: "memory")
; #define PG8_WAIT_L(n) asm volatile("s_waitcnt lgkmcnt(" #n ")" ::: "memory")
; #define PG8_BAR __builtin_amdgcn_s_barrier()
; template <class Epi, class Sched, bool ALIGN_EPI = false, bool SP2 = false>
; __device__ __forceinline__ void gemm_phase(LAS unsigned char* lds, const Gemm g, const Sched& S, const Epi& E) {
;     ...
;             const char* a1 = cA + (size_t)(t + 1) * kstep;
;             const char* a2 = last ? nA : cA + (size_t)(t + 2) * kstep; const char* b2 = last ? nB : cB + (size_t)(t + 2) * kstep;
;             const char* a3 = a2 + kstep; const char* b3 = b2 + kstep;
;             if (last && has_next) { S.a_ready(nxt); pre_nxt = E.pre(nxt, wr, fr); }
;             if constexpr (SP2) {
;             PG8_LDB(B0, 0, 0); PG8_LDB(B1, 0, 1); PG8_SCHED; PG8_LDA(At, 0, 0); PG8_STAGE(PG8_SA(1, 1), a1 + hstep, voffA);
;             PG8_WAIT_V(8); PG8_WAIT_L(0); PG8_BAR; PG8_MMA(0, 0, At, B0); PG8_MMA(0, 1, At, B1); PG8_BAR; PG8_SCHED;
;             PG8_LDA(At, 0, 1); PG8_STAGE(PG8_SB(0, 0), b2, voffB); PG8_STAGE(PG8_SB(0, 1), b2 + hstep, voffB); PG8_STAGE(PG8_SA(0, 0), a2, voffA);
;             PG8_WAIT_V(8); PG8_WAIT_L(0); PG8_BAR; PG8_MMA(1, 0, At, B0); PG8_MMA(1, 1, At, B1); PG8_BAR; PG8_SCHED;
.LBB0_146:
	v_add_u32_e32 v169, s70, v150
	ds_read_b128 v[170:173], v169
	ds_read_b128 v[178:181], v169 offset:1024
	ds_read_b128 v[182:185], v169 offset:2048
	ds_read_b128 v[190:193], v169 offset:3072
	v_add_u32_e32 v169, s71, v150
	ds_read_b128 v[194:197], v169
	ds_read_b128 v[198:201], v169 offset:1024
	ds_read_b128 v[202:205], v169 offset:2048
	ds_read_b128 v[206:209], v169 offset:3072
	s_add_u32 s48, s44, 0xfff80080
	s_addc_u32 s49, s45, -1
	s_and_b64 s[46:47], s[46:47], exec
	s_cselect_b32 s49, s29, s49
	s_cselect_b32 s48, s86, s48
	s_cselect_b32 s47, s11, s16
	s_cselect_b32 s46, s87, s88
	s_add_u32 s98, s46, 0x80
	s_addc_u32 s99, s47, 0
	s_add_u32 s100, s48, 0x80
	s_addc_u32 s101, s49, 0
	s_add_i32 m0, s43, 0xc000
	ds_read_b128 v[210:213], v152
	ds_read_b128 v[214:217], v152 offset:1024
	ds_read_b128 v[218:221], v152 offset:2048
	ds_read_b128 v[222:225], v152 offset:3072
	ds_read_b128 v[226:229], v152 offset:4096
	ds_read_b128 v[230:233], v152 offset:5120
	ds_read_b128 v[234:237], v152 offset:6144
	ds_read_b128 v[238:241], v152 offset:7168
	global_load_lds_dwordx4 v138, s[44:45]
	s_add_i32 m0, s43, 0xe000
	s_nop 0
	global_load_lds_dwordx4 v140, s[44:45]
	s_waitcnt vmcnt(8)
	s_waitcnt lgkmcnt(0)
	s_setprio 1
	s_barrier
	v_mfma_f32_16x16x32_bf16 v[124:127], v[170:173], v[210:213], v[124:127]
	v_mfma_f32_16x16x32_bf16 v[120:123], v[182:185], v[210:213], v[120:123]
	v_mfma_f32_16x16x32_bf16 v[108:111], v[170:173], v[218:221], v[108:111]
	v_mfma_f32_16x16x32_bf16 v[104:107], v[182:185], v[218:221], v[104:107]
	v_mfma_f32_16x16x32_bf16 v[92:95], v[170:173], v[226:229], v[92:95]
	v_mfma_f32_16x16x32_bf16 v[88:91], v[182:185], v[226:229], v[88:91]
	v_mfma_f32_16x16x32_bf16 v[76:79], v[170:173], v[234:237], v[76:79]
	v_mfma_f32_16x16x32_bf16 v[72:75], v[182:185], v[234:237], v[72:75]
	v_mfma_f32_16x16x32_bf16 v[124:127], v[178:181], v[214:217], v[124:127]
	v_mfma_f32_16x16x32_bf16 v[120:123], v[190:193], v[214:217], v[120:123]
	v_mfma_f32_16x16x32_bf16 v[108:111], v[178:181], v[222:225], v[108:111]
	v_mfma_f32_16x16x32_bf16 v[104:107], v[190:193], v[222:225], v[104:107]
	v_mfma_f32_16x16x32_bf16 v[92:95], v[178:181], v[230:233], v[92:95]
	v_mfma_f32_16x16x32_bf16 v[88:91], v[190:193], v[230:233], v[88:91]
	v_mfma_f32_16x16x32_bf16 v[76:79], v[178:181], v[238:241], v[76:79]
	v_mfma_f32_16x16x32_bf16 v[72:75], v[190:193], v[238:241], v[72:75]
	v_mfma_f32_16x16x32_bf16 v[116:119], v[194:197], v[210:213], v[116:119]
	v_mfma_f32_16x16x32_bf16 v[112:115], v[202:205], v[210:213], v[112:115]
	v_mfma_f32_16x16x32_bf16 v[100:103], v[194:197], v[218:221], v[100:103]
	v_mfma_f32_16x16x32_bf16 v[96:99], v[202:205], v[218:221], v[96:99]
	v_mfma_f32_16x16x32_bf16 v[84:87], v[194:197], v[226:229], v[84:87]
	v_mfma_f32_16x16x32_bf16 v[80:83], v[202:205], v[226:229], v[80:83]
	v_mfma_f32_16x16x32_bf16 v[68:71], v[194:197], v[234:237], v[68:71]
	v_mfma_f32_16x16x32_bf16 v[64:67], v[202:205], v[234:237], v[64:67]
	v_mfma_f32_16x16x32_bf16 v[116:119], v[198:201], v[214:217], v[116:119]
	v_mfma_f32_16x16x32_bf16 v[112:115], v[206:209], v[214:217], v[112:115]
	v_mfma_f32_16x16x32_bf16 v[100:103], v[198:201], v[222:225], v[100:103]
	v_mfma_f32_16x16x32_bf16 v[96:99], v[206:209], v[222:225], v[96:99]
	v_mfma_f32_16x16x32_bf16 v[84:87], v[198:201], v[230:233], v[84:87]
	v_mfma_f32_16x16x32_bf16 v[80:83], v[206:209], v[230:233], v[80:83]
	v_mfma_f32_16x16x32_bf16 v[68:71], v[198:201], v[238:241], v[68:71]
	v_mfma_f32_16x16x32_bf16 v[64:67], v[206:209], v[238:241], v[64:67]
	s_setprio 0
	s_barrier
	s_add_i32 s74, s70, s15
	s_mov_b32 m0, s74
	ds_read_b128 v[210:213], v152 offset:16384
	ds_read_b128 v[214:217], v152 offset:17408
	ds_read_b128 v[218:221], v152 offset:18432
	ds_read_b128 v[222:225], v152 offset:19456
	ds_read_b128 v[226:229], v152 offset:20480
	ds_read_b128 v[230:233], v152 offset:21504
	ds_read_b128 v[234:237], v152 offset:22528
	ds_read_b128 v[238:241], v152 offset:23552
	global_load_lds_dwordx4 v132, s[46:47]
	s_add_i32 m0, s74, 0x2000
	s_add_u32 s90, s46, 0x80000
	s_addc_u32 s91, s47, 0
	s_add_i32 s74, s71, s15
	global_load_lds_dwordx4 v128, s[46:47]
	s_mov_b32 m0, s74
	s_nop 0
	global_load_lds_dwordx4 v132, s[90:91]
	s_add_i32 m0, s74, 0x2000
	s_nop 0
	global_load_lds_dwordx4 v128, s[90:91]
	s_mov_b32 m0, s43
	s_nop 0
	global_load_lds_dwordx4 v134, s[48:49]
	s_mov_b32 m0, s50
	s_nop 0
	global_load_lds_dwordx4 v130, s[48:49]
	s_waitcnt vmcnt(8)
	s_waitcnt lgkmcnt(0)
	s_setprio 1
	s_barrier
	v_mfma_f32_16x16x32_bf16 v[60:63], v[170:173], v[210:213], v[60:63]
	v_mfma_f32_16x16x32_bf16 v[56:59], v[182:185], v[210:213], v[56:59]
	v_mfma_f32_16x16x32_bf16 v[44:47], v[170:173], v[218:221], v[44:47]
	v_mfma_f32_16x16x32_bf16 v[40:43], v[182:185], v[218:221], v[40:43]
	v_mfma_f32_16x16x32_bf16 v[28:31], v[170:173], v[226:229], v[28:31]
	v_mfma_f32_16x16x32_bf16 v[24:27], v[182:185], v[226:229], v[24:27]
	v_mfma_f32_16x16x32_bf16 v[12:15], v[170:173], v[234:237], v[12:15]
	v_mfma_f32_16x16x32_bf16 v[8:11], v[182:185], v[234:237], v[8:11]
	v_mfma_f32_16x16x32_bf16 v[60:63], v[178:181], v[214:217], v[60:63]
	v_mfma_f32_16x16x32_bf16 v[56:59], v[190:193], v[214:217], v[56:59]
	v_mfma_f32_16x16x32_bf16 v[44:47], v[178:181], v[222:225], v[44:47]
	v_mfma_f32_16x16x32_bf16 v[40:43], v[190:193], v[222:225], v[40:43]
	v_mfma_f32_16x16x32_bf16 v[28:31], v[178:181], v[230:233], v[28:31]
	v_mfma_f32_16x16x32_bf16 v[24:27], v[190:193], v[230:233], v[24:27]
	v_mfma_f32_16x16x32_bf16 v[12:15], v[178:181], v[238:241], v[12:15]
	v_mfma_f32_16x16x32_bf16 v[8:11], v[190:193], v[238:241], v[8:11]
	v_mfma_f32_16x16x32_bf16 v[52:55], v[194:197], v[210:213], v[52:55]
	v_mfma_f32_16x16x32_bf16 v[48:51], v[202:205], v[210:213], v[48:51]
	v_mfma_f32_16x16x32_bf16 v[36:39], v[194:197], v[218:221], v[36:39]
	v_mfma_f32_16x16x32_bf16 v[32:35], v[202:205], v[218:221], v[32:35]
	v_mfma_f32_16x16x32_bf16 v[20:23], v[194:197], v[226:229], v[20:23]
	v_mfma_f32_16x16x32_bf16 v[16:19], v[202:205], v[226:229], v[16:19]
	v_mfma_f32_16x16x32_bf16 v[4:7], v[194:197], v[234:237], v[4:7]
	v_mfma_f32_16x16x32_bf16 v[0:3], v[202:205], v[234:237], v[0:3]
	v_mfma_f32_16x16x32_bf16 v[52:55], v[198:201], v[214:217], v[52:55]
	v_mfma_f32_16x16x32_bf16 v[48:51], v[206:209], v[214:217], v[48:51]
	v_mfma_f32_16x16x32_bf16 v[36:39], v[198:201], v[222:225], v[36:39]
	v_mfma_f32_16x16x32_bf16 v[32:35], v[206:209], v[222:225], v[32:35]
	v_mfma_f32_16x16x32_bf16 v[20:23], v[198:201], v[230:233], v[20:23]
	v_mfma_f32_16x16x32_bf16 v[16:19], v[206:209], v[230:233], v[16:19]
	v_mfma_f32_16x16x32_bf16 v[4:7], v[198:201], v[238:241], v[4:7]
	v_mfma_f32_16x16x32_bf16 v[0:3], v[206:209], v[238:241], v[0:3]
	s_setprio 0
	s_barrier
; #define PG8_STAGE(bufoff, gbase, voff) do { _Pragma("unroll") for (int _i = 0; _i < 2; ++_i) \
;         __builtin_amdgcn_global_load_lds((const unsigned*)((const char*)(gbase) + (voff)[_i]), (LAS unsigned*)(lds + (bufoff) + ldsw + _i * 8192), 16, 0, 0); } while (0)
; #define PG8_LDA(dst, b, h) do { _Pragma("unroll") for (int m = 0; m < 4; ++m) _Pragma("unroll") for (int k = 0; k < 2; ++k) dst[m][k] = *(const LAS bf16x8*)(lds + PG8_SA(b, h) + aoff + m * 2048 + k * 1024); } while (0)
; #define PG8_LDB(dst, b, h) do { _Pragma("unroll") for (int n = 0; n < 2; ++n) _Pragma("unroll") for (int k = 0; k < 2; ++k) dst[n][k] = *(const LAS bf16x8*)(lds + PG8_SB(b, h) + boff + n * 2048 + k * 1024); } while (0)
; #define PG8_MMA(ai, bj, At, Bt) do { __builtin_amdgcn_s_setprio(1); _Pragma("unroll") for (int m = 0; m < 4; ++m) _Pragma("unroll") for (int n = 0; n < 2; ++n) _Pragma("unroll") for (int k = 0; k < 2; ++k) \
;         acc[ai][bj][m][n] = __builtin_amdgcn_mfma_f32_16x16x32_bf16(Bt[n][k], At[m][k], acc[ai][bj][m][n], 0, 0, 0); __builtin_amdgcn_s_setprio(0); } while (0)
; #define PG8_WAIT_V(n) asm volatile("s_waitcnt vmcnt(" #n ")" ::: "memory")
; #define PG8_WAIT_L(n) asm volatile("s_waitcnt lgkmcnt(" #n ")" ::: "memory")
; #define PG8_BAR __builtin_amdgcn_s_barrier()
; #define PG8_SCHED __builtin_amdgcn_sched_barrier(0)
; template <class Epi, class Sched, bool ALIGN_EPI = false, bool SP2 = false>
; __device__ __forceinline__ void gemm_phase(LAS unsigned char* lds, const Gemm g, const Sched& S, const Epi& E) {
;     ...
;             PG8_LDB(B0, 1, 0); PG8_LDB(B1, 1, 1); PG8_SCHED; PG8_LDA(At, 1, 0); PG8_STAGE(PG8_SA(0, 1), a2 + hstep, voffA);
;             PG8_WAIT_V(8); PG8_WAIT_L(0); PG8_BAR; PG8_MMA(0, 0, At, B0); PG8_MMA(0, 1, At, B1); PG8_BAR; PG8_SCHED;
;             PG8_LDA(At, 1, 1); PG8_STAGE(PG8_SB(1, 0), b3, voffB); PG8_STAGE(PG8_SB(1, 1), b3 + hstep, voffB); PG8_STAGE(PG8_SA(1, 0), a3, voffA);
;             PG8_WAIT_V(8); PG8_WAIT_L(0); PG8_BAR; PG8_MMA(1, 0, At, B0); PG8_MMA(1, 1, At, B1); PG8_BAR; PG8_SCHED;
	s_add_i32 s74, 0, 0x18000
	v_add_u32_e32 v169, s74, v150
	s_add_i32 s89, 0, 0x1c000
	ds_read_b128 v[170:173], v169
	ds_read_b128 v[178:181], v169 offset:1024
	ds_read_b128 v[182:185], v169 offset:2048
	ds_read_b128 v[190:193], v169 offset:3072
	v_add_u32_e32 v169, s89, v150
	ds_read_b128 v[194:197], v169
	ds_read_b128 v[198:201], v169 offset:1024
	ds_read_b128 v[202:205], v169 offset:2048
	ds_read_b128 v[206:209], v169 offset:3072
	s_add_u32 s48, s48, 0x80000
	s_addc_u32 s49, s49, 0
	s_mov_b32 m0, s51
	ds_read_b128 v[210:213], v152 offset:32768
	ds_read_b128 v[214:217], v152 offset:33792
	ds_read_b128 v[218:221], v152 offset:34816
	ds_read_b128 v[222:225], v152 offset:35840
	ds_read_b128 v[226:229], v152 offset:36864
	ds_read_b128 v[230:233], v152 offset:37888
	ds_read_b128 v[234:237], v152 offset:38912
	ds_read_b128 v[238:241], v152 offset:39936
	global_load_lds_dwordx4 v134, s[48:49]
	s_mov_b32 m0, s66
	s_nop 0
	global_load_lds_dwordx4 v130, s[48:49]
	s_waitcnt vmcnt(8)
	s_waitcnt lgkmcnt(0)
	s_setprio 1
	s_barrier
	v_mfma_f32_16x16x32_bf16 v[124:127], v[170:173], v[210:213], v[124:127]
	v_mfma_f32_16x16x32_bf16 v[120:123], v[182:185], v[210:213], v[120:123]
	v_mfma_f32_16x16x32_bf16 v[108:111], v[170:173], v[218:221], v[108:111]
	v_mfma_f32_16x16x32_bf16 v[104:107], v[182:185], v[218:221], v[104:107]
	v_mfma_f32_16x16x32_bf16 v[92:95], v[170:173], v[226:229], v[92:95]
	v_mfma_f32_16x16x32_bf16 v[88:91], v[182:185], v[226:229], v[88:91]
	v_mfma_f32_16x16x32_bf16 v[76:79], v[170:173], v[234:237], v[76:79]
	v_mfma_f32_16x16x32_bf16 v[72:75], v[182:185], v[234:237], v[72:75]
	v_mfma_f32_16x16x32_bf16 v[124:127], v[178:181], v[214:217], v[124:127]
	v_mfma_f32_16x16x32_bf16 v[120:123], v[190:193], v[214:217], v[120:123]
	v_mfma_f32_16x16x32_bf16 v[108:111], v[178:181], v[222:225], v[108:111]
	v_mfma_f32_16x16x32_bf16 v[104:107], v[190:193], v[222:225], v[104:107]
	v_mfma_f32_16x16x32_bf16 v[92:95], v[178:181], v[230:233], v[92:95]
	v_mfma_f32_16x16x32_bf16 v[88:91], v[190:193], v[230:233], v[88:91]
	v_mfma_f32_16x16x32_bf16 v[76:79], v[178:181], v[238:241], v[76:79]
	v_mfma_f32_16x16x32_bf16 v[72:75], v[190:193], v[238:241], v[72:75]
	v_mfma_f32_16x16x32_bf16 v[116:119], v[194:197], v[210:213], v[116:119]
	v_mfma_f32_16x16x32_bf16 v[112:115], v[202:205], v[210:213], v[112:115]
	v_mfma_f32_16x16x32_bf16 v[100:103], v[194:197], v[218:221], v[100:103]
	v_mfma_f32_16x16x32_bf16 v[96:99], v[202:205], v[218:221], v[96:99]
	v_mfma_f32_16x16x32_bf16 v[84:87], v[194:197], v[226:229], v[84:87]
	v_mfma_f32_16x16x32_bf16 v[80:83], v[202:205], v[226:229], v[80:83]
	v_mfma_f32_16x16x32_bf16 v[68:71], v[194:197], v[234:237], v[68:71]
	v_mfma_f32_16x16x32_bf16 v[64:67], v[202:205], v[234:237], v[64:67]
	v_mfma_f32_16x16x32_bf16 v[116:119], v[198:201], v[214:217], v[116:119]
	v_mfma_f32_16x16x32_bf16 v[112:115], v[206:209], v[214:217], v[112:115]
	v_mfma_f32_16x16x32_bf16 v[100:103], v[198:201], v[222:225], v[100:103]
	v_mfma_f32_16x16x32_bf16 v[96:99], v[206:209], v[222:225], v[96:99]
	v_mfma_f32_16x16x32_bf16 v[84:87], v[198:201], v[230:233], v[84:87]
	v_mfma_f32_16x16x32_bf16 v[80:83], v[206:209], v[230:233], v[80:83]
	v_mfma_f32_16x16x32_bf16 v[68:71], v[198:201], v[238:241], v[68:71]
	v_mfma_f32_16x16x32_bf16 v[64:67], v[206:209], v[238:241], v[64:67]
	s_setprio 0
	s_barrier
	s_add_i32 s48, s74, s15
	s_mov_b32 m0, s48
	ds_read_b128 v[210:213], v152 offset:49152
	ds_read_b128 v[214:217], v152 offset:50176
	ds_read_b128 v[218:221], v152 offset:51200
	ds_read_b128 v[222:225], v152 offset:52224
	ds_read_b128 v[226:229], v152 offset:53248
	ds_read_b128 v[230:233], v152 offset:54272
	ds_read_b128 v[234:237], v152 offset:55296
	ds_read_b128 v[238:241], v152 offset:56320
	global_load_lds_dwordx4 v132, s[98:99]
	s_add_i32 m0, s48, 0x2000
	s_add_u32 s46, s46, 0x80080
	s_addc_u32 s47, s47, 0
	s_add_i32 s48, s89, s15
	global_load_lds_dwordx4 v128, s[98:99]
	s_mov_b32 m0, s48
	s_nop 0
	global_load_lds_dwordx4 v132, s[46:47]
	s_add_i32 m0, s48, 0x2000
	s_nop 0
	global_load_lds_dwordx4 v128, s[46:47]
	s_mov_b32 m0, s68
	s_nop 0
	global_load_lds_dwordx4 v134, s[100:101]
	s_mov_b32 m0, s69
	s_nop 0
	global_load_lds_dwordx4 v130, s[100:101]
	s_waitcnt vmcnt(8)
	s_waitcnt lgkmcnt(0)
	s_setprio 1
	s_barrier
	v_mfma_f32_16x16x32_bf16 v[60:63], v[170:173], v[210:213], v[60:63]
	v_mfma_f32_16x16x32_bf16 v[56:59], v[182:185], v[210:213], v[56:59]
	v_mfma_f32_16x16x32_bf16 v[44:47], v[170:173], v[218:221], v[44:47]
	v_mfma_f32_16x16x32_bf16 v[40:43], v[182:185], v[218:221], v[40:43]
	v_mfma_f32_16x16x32_bf16 v[28:31], v[170:173], v[226:229], v[28:31]
	v_mfma_f32_16x16x32_bf16 v[24:27], v[182:185], v[226:229], v[24:27]
	v_mfma_f32_16x16x32_bf16 v[12:15], v[170:173], v[234:237], v[12:15]
	v_mfma_f32_16x16x32_bf16 v[8:11], v[182:185], v[234:237], v[8:11]
	v_mfma_f32_16x16x32_bf16 v[60:63], v[178:181], v[214:217], v[60:63]
	v_mfma_f32_16x16x32_bf16 v[56:59], v[190:193], v[214:217], v[56:59]
	v_mfma_f32_16x16x32_bf16 v[44:47], v[178:181], v[222:225], v[44:47]
	v_mfma_f32_16x16x32_bf16 v[40:43], v[190:193], v[222:225], v[40:43]
	v_mfma_f32_16x16x32_bf16 v[28:31], v[178:181], v[230:233], v[28:31]
	v_mfma_f32_16x16x32_bf16 v[24:27], v[190:193], v[230:233], v[24:27]
	v_mfma_f32_16x16x32_bf16 v[12:15], v[178:181], v[238:241], v[12:15]
	v_mfma_f32_16x16x32_bf16 v[8:11], v[190:193], v[238:241], v[8:11]
	v_mfma_f32_16x16x32_bf16 v[52:55], v[194:197], v[210:213], v[52:55]
	v_mfma_f32_16x16x32_bf16 v[48:51], v[202:205], v[210:213], v[48:51]
	v_mfma_f32_16x16x32_bf16 v[36:39], v[194:197], v[218:221], v[36:39]
	v_mfma_f32_16x16x32_bf16 v[32:35], v[202:205], v[218:221], v[32:35]
	v_mfma_f32_16x16x32_bf16 v[20:23], v[194:197], v[226:229], v[20:23]
	v_mfma_f32_16x16x32_bf16 v[16:19], v[202:205], v[226:229], v[16:19]
	v_mfma_f32_16x16x32_bf16 v[4:7], v[194:197], v[234:237], v[4:7]
	v_mfma_f32_16x16x32_bf16 v[0:3], v[202:205], v[234:237], v[0:3]
	v_mfma_f32_16x16x32_bf16 v[52:55], v[198:201], v[214:217], v[52:55]
	v_mfma_f32_16x16x32_bf16 v[48:51], v[206:209], v[214:217], v[48:51]
	v_mfma_f32_16x16x32_bf16 v[36:39], v[198:201], v[222:225], v[36:39]
	v_mfma_f32_16x16x32_bf16 v[32:35], v[206:209], v[222:225], v[32:35]
	v_mfma_f32_16x16x32_bf16 v[20:23], v[198:201], v[230:233], v[20:23]
	v_mfma_f32_16x16x32_bf16 v[16:19], v[206:209], v[230:233], v[16:19]
	v_mfma_f32_16x16x32_bf16 v[4:7], v[198:201], v[238:241], v[4:7]
	v_mfma_f32_16x16x32_bf16 v[0:3], v[206:209], v[238:241], v[0:3]
	s_setprio 0
	s_barrier
	s_add_i32 s17, s17, 2
	s_add_u32 s44, s44, 0x100
	s_addc_u32 s45, s45, 0
	s_add_u32 s88, s88, 0x100
	s_addc_u32 s16, s16, 0
	s_cmp_gt_u32 s17, 29
	s_cbranch_scc1 .LBB0_149
;     __device__ __forceinline__ Pre pre(const Unit& u, int wr, int fr) const { return load_rows8(ss, u, wr, fr); }
;     __device__ __forceinline__ Pre pre(const Unit& u, int wr, int fr) const { return load_rows8(ss, u, wr, fr); }
; template <class Epi, class Sched, bool ALIGN_EPI = false, bool SP2 = false>
; __device__ __forceinline__ void gemm_phase(LAS unsigned char* lds, const Gemm g, const Sched& S, const Epi& E) {
;     ...
;             const bool last = (t == nt - 2);
;             const char* a1 = cA + (size_t)(t + 1) * kstep;
;             const char* a2 = last ? nA : cA + (size_t)(t + 2) * kstep; const char* b2 = last ? nB : cB + (size_t)(t + 2) * kstep;
;             const char* a3 = a2 + kstep; const char* b3 = b2 + kstep;
;             if (last && has_next) { S.a_ready(nxt); pre_nxt = E.pre(nxt, wr, fr); }
; __device__ __forceinline__ PreRows load_rows8(const float* ss, const Unit& u, int wr, int fr) {
;     PreRows p; const float* b = ss + u.pm * BM + wr * 64 + fr;
; #pragma unroll
;     for (int ai = 0; ai < 2; ++ai)
; #pragma unroll
;         for (int m = 0; m < 4; ++m) p.v[ai * 4 + m] = b[ai * HALF + m * 16];
;     return p;
.LBB0_147:
	s_cmp_eq_u32 s17, 28
	s_cselect_b64 s[46:47], -1, 0
	s_and_b64 s[48:49], s[4:5], s[46:47]
	s_andn2_b64 vcc, exec, s[48:49]
	s_cbranch_vccnz .LBB0_146
	global_load_dword v155, v[146:147], off
	global_load_dword v156, v[146:147], off offset:64
	global_load_dword v157, v[146:147], off offset:128
	global_load_dword v158, v[146:147], off offset:192
	global_load_dword v159, v[146:147], off offset:512
	global_load_dword v160, v[146:147], off offset:576
	global_load_dword v162, v[146:147], off offset:640
	global_load_dword v163, v[146:147], off offset:704
	s_branch .LBB0_146
	s_nop 0
	s_nop 0
	s_nop 0
	s_nop 0
	s_nop 0
	s_nop 0
	s_nop 0
	s_nop 0
	s_nop 0
	s_nop 0
	s_nop 0
	s_nop 0
	s_nop 0
	s_nop 0
	s_nop 0
	s_nop 0
	s_nop 0
	s_nop 0
	s_nop 0
	s_nop 0
	s_nop 0
	s_nop 0
	s_nop 0
	s_nop 0
	s_nop 0
	s_nop 0
	s_nop 0
	s_nop 0
	s_nop 0
	s_nop 0
	s_nop 0
	s_nop 0
	s_nop 0
	s_nop 0
	s_nop 0
	s_nop 0
	s_nop 0

; #define PG8_STAGE(bufoff, gbase, voff) do { _Pragma("unroll") for (int _i = 0; _i < 2; ++_i) \
;         __builtin_amdgcn_global_load_lds((const unsigned*)((const char*)(gbase) + (voff)[_i]), (LAS unsigned*)(lds + (bufoff) + ldsw + _i * 8192), 16, 0, 0); } while (0)
; #define PG8_LDA(dst, b, h) do { _Pragma("unroll") for (int m = 0; m < 4; ++m) _Pragma("unroll") for (int k = 0; k < 2; ++k) dst[m][k] = *(const LAS bf16x8*)(lds + PG8_SA(b, h) + aoff + m * 2048 + k * 1024); } while (0)
; #define PG8_LDB(dst, b, h) do { _Pragma("unroll") for (int n = 0; n < 2; ++n) _Pragma("unroll") for (int k = 0; k < 2; ++k) dst[n][k] = *(const LAS bf16x8*)(lds + PG8_SB(b, h) + boff + n * 2048 + k * 1024); } while (0)
; #define PG8_MMA(ai, bj, At, Bt) do { __builtin_amdgcn_s_setprio(1); _Pragma("unroll") for (int m = 0; m < 4; ++m) _Pragma("unroll") for (int n = 0; n < 2; ++n) _Pragma("unroll") for (int k = 0; k < 2; ++k) \
;         acc[ai][bj][m][n] = __builtin_amdgcn_mfma_f32_16x16x32_bf16(Bt[n][k], At[m][k], acc[ai][bj][m][n], 0, 0, 0); __builtin_amdgcn_s_setprio(0); } while (0)
; #define PG8_WAIT_V(n) asm volatile("s_waitcnt vmcnt(" #n ")" ::: "memory")
; #define PG8_WAIT_L(n) asm volatile("s_waitcnt lgkmcnt(" #n ")" ::: "memory")
; #define PG8_BAR __builtin_amdgcn_s_barrier()
; #define PG8_SCHED __builtin_amdgcn_sched_barrier(0)
; template <class Epi, class Sched, bool ALIGN_EPI = false, bool SP2 = false>
; __device__ __forceinline__ void gemm_phase(LAS unsigned char* lds, const Gemm g, const Sched& S, const Epi& E) {
;     ...
;             if constexpr (SP2) {
;             PG8_LDB(B0, 0, 0); PG8_LDB(B1, 0, 1); PG8_SCHED; PG8_LDA(At, 0, 0); PG8_STAGE(PG8_SA(1, 1), a1 + hstep, voffA);
;             PG8_WAIT_V(8); PG8_WAIT_L(0); PG8_BAR; PG8_MMA(0, 0, At, B0); PG8_MMA(0, 1, At, B1); PG8_BAR; PG8_SCHED;
;             PG8_LDA(At, 0, 1); PG8_STAGE(PG8_SB(0, 0), b2, voffB); PG8_STAGE(PG8_SB(0, 1), b2 + hstep, voffB); PG8_STAGE(PG8_SA(0, 0), a2, voffA);
;             PG8_WAIT_V(8); PG8_WAIT_L(0); PG8_BAR; PG8_MMA(1, 0, At, B0); PG8_MMA(1, 1, At, B1); PG8_BAR; PG8_SCHED;
.LBB0_231:
	ds_read_b128 v[128:131], v192
	ds_read_b128 v[132:135], v192 offset:1024
	ds_read_b128 v[136:139], v192 offset:2048
	ds_read_b128 v[140:143], v192 offset:3072
	ds_read_b128 v[144:147], v193
	ds_read_b128 v[148:151], v193 offset:1024
	ds_read_b128 v[168:171], v193 offset:2048
	ds_read_b128 v[172:175], v193 offset:3072
	s_add_u32 s44, s42, 0x100
	s_addc_u32 s45, s43, 0
	s_cmpk_eq_i32 s86, 0x54
	s_cselect_b32 s49, s1, s45
	s_cselect_b32 s48, s0, s44
	s_cselect_b32 s47, s41, s17
	s_cselect_b32 s46, s40, s16
	s_add_i32 m0, s35, 0xc000
	ds_read_b128 v[178:181], v194
	ds_read_b128 v[182:185], v194 offset:1024
	ds_read_b128 v[196:199], v194 offset:2048
	ds_read_b128 v[200:203], v194 offset:3072
	ds_read_b128 v[204:207], v194 offset:4096
	ds_read_b128 v[208:211], v194 offset:5120
	ds_read_b128 v[212:215], v194 offset:6144
	ds_read_b128 v[216:219], v194 offset:7168
	global_load_lds_dwordx4 v160, s[42:43]
	s_add_i32 m0, s35, 0xe000
	s_nop 0
	global_load_lds_dwordx4 v162, s[42:43]
	s_waitcnt vmcnt(8)
	s_waitcnt lgkmcnt(0)
	s_setprio 1
	s_barrier
	v_mfma_f32_16x16x32_bf16 v[124:127], v[128:131], v[178:181], v[124:127]
	v_mfma_f32_16x16x32_bf16 v[120:123], v[136:139], v[178:181], v[120:123]
	v_mfma_f32_16x16x32_bf16 v[108:111], v[128:131], v[196:199], v[108:111]
	v_mfma_f32_16x16x32_bf16 v[104:107], v[136:139], v[196:199], v[104:107]
	v_mfma_f32_16x16x32_bf16 v[92:95], v[128:131], v[204:207], v[92:95]
	v_mfma_f32_16x16x32_bf16 v[88:91], v[136:139], v[204:207], v[88:91]
	v_mfma_f32_16x16x32_bf16 v[76:79], v[128:131], v[212:215], v[76:79]
	v_mfma_f32_16x16x32_bf16 v[72:75], v[136:139], v[212:215], v[72:75]
	v_mfma_f32_16x16x32_bf16 v[124:127], v[132:135], v[182:185], v[124:127]
	v_mfma_f32_16x16x32_bf16 v[120:123], v[140:143], v[182:185], v[120:123]
	v_mfma_f32_16x16x32_bf16 v[108:111], v[132:135], v[200:203], v[108:111]
	v_mfma_f32_16x16x32_bf16 v[104:107], v[140:143], v[200:203], v[104:107]
	v_mfma_f32_16x16x32_bf16 v[92:95], v[132:135], v[208:211], v[92:95]
	v_mfma_f32_16x16x32_bf16 v[88:91], v[140:143], v[208:211], v[88:91]
	v_mfma_f32_16x16x32_bf16 v[76:79], v[132:135], v[216:219], v[76:79]
	v_mfma_f32_16x16x32_bf16 v[72:75], v[140:143], v[216:219], v[72:75]
	v_mfma_f32_16x16x32_bf16 v[116:119], v[144:147], v[178:181], v[116:119]
	v_mfma_f32_16x16x32_bf16 v[112:115], v[168:171], v[178:181], v[112:115]
	v_mfma_f32_16x16x32_bf16 v[100:103], v[144:147], v[196:199], v[100:103]
	v_mfma_f32_16x16x32_bf16 v[96:99], v[168:171], v[196:199], v[96:99]
	v_mfma_f32_16x16x32_bf16 v[84:87], v[144:147], v[204:207], v[84:87]
	v_mfma_f32_16x16x32_bf16 v[80:83], v[168:171], v[204:207], v[80:83]
	v_mfma_f32_16x16x32_bf16 v[68:71], v[144:147], v[212:215], v[68:71]
	v_mfma_f32_16x16x32_bf16 v[64:67], v[168:171], v[212:215], v[64:67]
	v_mfma_f32_16x16x32_bf16 v[116:119], v[148:151], v[182:185], v[116:119]
	v_mfma_f32_16x16x32_bf16 v[112:115], v[172:175], v[182:185], v[112:115]
	v_mfma_f32_16x16x32_bf16 v[100:103], v[148:151], v[200:203], v[100:103]
	v_mfma_f32_16x16x32_bf16 v[96:99], v[172:175], v[200:203], v[96:99]
	v_mfma_f32_16x16x32_bf16 v[84:87], v[148:151], v[208:211], v[84:87]
	v_mfma_f32_16x16x32_bf16 v[80:83], v[172:175], v[208:211], v[80:83]
	v_mfma_f32_16x16x32_bf16 v[68:71], v[148:151], v[216:219], v[68:71]
	v_mfma_f32_16x16x32_bf16 v[64:67], v[172:175], v[216:219], v[64:67]
	s_setprio 0
	s_barrier
	s_add_u32 s100, s48, 0x80
	s_addc_u32 s101, s49, 0
	s_add_u32 s98, s46, 0x80
	s_addc_u32 s99, s47, 0
	s_add_i32 s42, s68, s15
	s_mov_b32 m0, s42
	ds_read_b128 v[178:181], v194 offset:16384
	ds_read_b128 v[182:185], v194 offset:17408
	ds_read_b128 v[196:199], v194 offset:18432
	ds_read_b128 v[200:203], v194 offset:19456
	ds_read_b128 v[204:207], v194 offset:20480
	ds_read_b128 v[208:211], v194 offset:21504
	ds_read_b128 v[212:215], v194 offset:22528
	ds_read_b128 v[216:219], v194 offset:23552
	global_load_lds_dwordx4 v154, s[46:47]
	s_add_i32 m0, s42, 0x2000
	s_add_u32 s42, s46, 0x160000
	s_addc_u32 s43, s47, 0
	s_add_i32 s74, s69, s15
	global_load_lds_dwordx4 v158, s[46:47]
	s_mov_b32 m0, s74
	s_nop 0
	global_load_lds_dwordx4 v154, s[42:43]
	s_add_i32 m0, s74, 0x2000
	s_nop 0
	global_load_lds_dwordx4 v158, s[42:43]
	s_mov_b32 m0, s35
	s_nop 0
	global_load_lds_dwordx4 v152, s[48:49]
	s_mov_b32 m0, s50
	s_nop 0
	global_load_lds_dwordx4 v156, s[48:49]
	s_waitcnt vmcnt(8)
	s_waitcnt lgkmcnt(0)
	s_setprio 1
	s_barrier
	v_mfma_f32_16x16x32_bf16 v[60:63], v[128:131], v[178:181], v[60:63]
	v_mfma_f32_16x16x32_bf16 v[56:59], v[136:139], v[178:181], v[56:59]
	v_mfma_f32_16x16x32_bf16 v[44:47], v[128:131], v[196:199], v[44:47]
	v_mfma_f32_16x16x32_bf16 v[40:43], v[136:139], v[196:199], v[40:43]
	v_mfma_f32_16x16x32_bf16 v[28:31], v[128:131], v[204:207], v[28:31]
	v_mfma_f32_16x16x32_bf16 v[24:27], v[136:139], v[204:207], v[24:27]
	v_mfma_f32_16x16x32_bf16 v[12:15], v[128:131], v[212:215], v[12:15]
	v_mfma_f32_16x16x32_bf16 v[8:11], v[136:139], v[212:215], v[8:11]
	v_mfma_f32_16x16x32_bf16 v[60:63], v[132:135], v[182:185], v[60:63]
	v_mfma_f32_16x16x32_bf16 v[56:59], v[140:143], v[182:185], v[56:59]
	v_mfma_f32_16x16x32_bf16 v[44:47], v[132:135], v[200:203], v[44:47]
	v_mfma_f32_16x16x32_bf16 v[40:43], v[140:143], v[200:203], v[40:43]
	v_mfma_f32_16x16x32_bf16 v[28:31], v[132:135], v[208:211], v[28:31]
	v_mfma_f32_16x16x32_bf16 v[24:27], v[140:143], v[208:211], v[24:27]
	v_mfma_f32_16x16x32_bf16 v[12:15], v[132:135], v[216:219], v[12:15]
	v_mfma_f32_16x16x32_bf16 v[8:11], v[140:143], v[216:219], v[8:11]
	v_mfma_f32_16x16x32_bf16 v[52:55], v[144:147], v[178:181], v[52:55]
	v_mfma_f32_16x16x32_bf16 v[48:51], v[168:171], v[178:181], v[48:51]
	v_mfma_f32_16x16x32_bf16 v[36:39], v[144:147], v[196:199], v[36:39]
	v_mfma_f32_16x16x32_bf16 v[32:35], v[168:171], v[196:199], v[32:35]
	v_mfma_f32_16x16x32_bf16 v[20:23], v[144:147], v[204:207], v[20:23]
	v_mfma_f32_16x16x32_bf16 v[16:19], v[168:171], v[204:207], v[16:19]
	v_mfma_f32_16x16x32_bf16 v[4:7], v[144:147], v[212:215], v[4:7]
	v_mfma_f32_16x16x32_bf16 v[0:3], v[168:171], v[212:215], v[0:3]
	v_mfma_f32_16x16x32_bf16 v[52:55], v[148:151], v[182:185], v[52:55]
	v_mfma_f32_16x16x32_bf16 v[48:51], v[172:175], v[182:185], v[48:51]
	v_mfma_f32_16x16x32_bf16 v[36:39], v[148:151], v[200:203], v[36:39]
	v_mfma_f32_16x16x32_bf16 v[32:35], v[172:175], v[200:203], v[32:35]
	v_mfma_f32_16x16x32_bf16 v[20:23], v[148:151], v[208:211], v[20:23]
	v_mfma_f32_16x16x32_bf16 v[16:19], v[172:175], v[208:211], v[16:19]
	v_mfma_f32_16x16x32_bf16 v[4:7], v[148:151], v[216:219], v[4:7]
	v_mfma_f32_16x16x32_bf16 v[0:3], v[172:175], v[216:219], v[0:3]
	s_setprio 0
	s_barrier
; #define PG8_STAGE(bufoff, gbase, voff) do { _Pragma("unroll") for (int _i = 0; _i < 2; ++_i) \
;         __builtin_amdgcn_global_load_lds((const unsigned*)((const char*)(gbase) + (voff)[_i]), (LAS unsigned*)(lds + (bufoff) + ldsw + _i * 8192), 16, 0, 0); } while (0)
; #define PG8_LDA(dst, b, h) do { _Pragma("unroll") for (int m = 0; m < 4; ++m) _Pragma("unroll") for (int k = 0; k < 2; ++k) dst[m][k] = *(const LAS bf16x8*)(lds + PG8_SA(b, h) + aoff + m * 2048 + k * 1024); } while (0)
; #define PG8_LDB(dst, b, h) do { _Pragma("unroll") for (int n = 0; n < 2; ++n) _Pragma("unroll") for (int k = 0; k < 2; ++k) dst[n][k] = *(const LAS bf16x8*)(lds + PG8_SB(b, h) + boff + n * 2048 + k * 1024); } while (0)
; #define PG8_MMA(ai, bj, At, Bt) do { __builtin_amdgcn_s_setprio(1); _Pragma("unroll") for (int m = 0; m < 4; ++m) _Pragma("unroll") for (int n = 0; n < 2; ++n) _Pragma("unroll") for (int k = 0; k < 2; ++k) \
;         acc[ai][bj][m][n] = __builtin_amdgcn_mfma_f32_16x16x32_bf16(Bt[n][k], At[m][k], acc[ai][bj][m][n], 0, 0, 0); __builtin_amdgcn_s_setprio(0); } while (0)
; #define PG8_WAIT_V(n) asm volatile("s_waitcnt vmcnt(" #n ")" ::: "memory")
; #define PG8_WAIT_L(n) asm volatile("s_waitcnt lgkmcnt(" #n ")" ::: "memory")
; #define PG8_BAR __builtin_amdgcn_s_barrier()
; #define PG8_SCHED __builtin_amdgcn_sched_barrier(0)
; template <class Epi, class Sched, bool ALIGN_EPI = false, bool SP2 = false>
; __device__ __forceinline__ void gemm_phase(LAS unsigned char* lds, const Gemm g, const Sched& S, const Epi& E) {
;     ...
;         for (int t = 0; t < nt; t += 2) {
;             const bool last = (t == nt - 2);
;             const char* a1 = cA + (size_t)(t + 1) * kstep;
;             const char* a2 = last ? nA : cA + (size_t)(t + 2) * kstep; const char* b2 = last ? nB : cB + (size_t)(t + 2) * kstep;
;     ...
;             PG8_LDB(B0, 1, 0); PG8_LDB(B1, 1, 1); PG8_SCHED; PG8_LDA(At, 1, 0); PG8_STAGE(PG8_SA(0, 1), a2 + hstep, voffA);
;             PG8_WAIT_V(8); PG8_WAIT_L(0); PG8_BAR; PG8_MMA(0, 0, At, B0); PG8_MMA(0, 1, At, B1); PG8_BAR; PG8_SCHED;
;             PG8_LDA(At, 1, 1); PG8_STAGE(PG8_SB(1, 0), b3, voffB); PG8_STAGE(PG8_SB(1, 1), b3 + hstep, voffB); PG8_STAGE(PG8_SA(1, 0), a3, voffA);
;             PG8_WAIT_V(8); PG8_WAIT_L(0); PG8_BAR; PG8_MMA(1, 0, At, B0); PG8_MMA(1, 1, At, B1); PG8_BAR; PG8_SCHED;
	s_add_i32 s74, 0, 0x18000
	s_add_i32 s87, 0, 0x1c000
	v_add_u32_e32 v140, s74, v190
	v_add_u32_e32 v172, s87, v190
	ds_read_b128 v[128:131], v140
	ds_read_b128 v[132:135], v140 offset:1024
	ds_read_b128 v[136:139], v140 offset:2048
	ds_read_b128 v[140:143], v140 offset:3072
	ds_read_b128 v[144:147], v172
	ds_read_b128 v[148:151], v172 offset:1024
	ds_read_b128 v[168:171], v172 offset:2048
	ds_read_b128 v[172:175], v172 offset:3072
	s_add_u32 s42, s48, 0x160000
	s_addc_u32 s43, s49, 0
	s_mov_b32 m0, s51
	ds_read_b128 v[178:181], v194 offset:32768
	ds_read_b128 v[182:185], v194 offset:33792
	ds_read_b128 v[196:199], v194 offset:34816
	ds_read_b128 v[200:203], v194 offset:35840
	ds_read_b128 v[204:207], v194 offset:36864
	ds_read_b128 v[208:211], v194 offset:37888
	ds_read_b128 v[212:215], v194 offset:38912
	ds_read_b128 v[216:219], v194 offset:39936
	global_load_lds_dwordx4 v152, s[42:43]
	s_mov_b32 m0, s64
	s_nop 0
	global_load_lds_dwordx4 v156, s[42:43]
	s_waitcnt vmcnt(8)
	s_waitcnt lgkmcnt(0)
	s_setprio 1
	s_barrier
	v_mfma_f32_16x16x32_bf16 v[124:127], v[128:131], v[178:181], v[124:127]
	v_mfma_f32_16x16x32_bf16 v[120:123], v[136:139], v[178:181], v[120:123]
	v_mfma_f32_16x16x32_bf16 v[108:111], v[128:131], v[196:199], v[108:111]
	v_mfma_f32_16x16x32_bf16 v[104:107], v[136:139], v[196:199], v[104:107]
	v_mfma_f32_16x16x32_bf16 v[92:95], v[128:131], v[204:207], v[92:95]
	v_mfma_f32_16x16x32_bf16 v[88:91], v[136:139], v[204:207], v[88:91]
	v_mfma_f32_16x16x32_bf16 v[76:79], v[128:131], v[212:215], v[76:79]
	v_mfma_f32_16x16x32_bf16 v[72:75], v[136:139], v[212:215], v[72:75]
	v_mfma_f32_16x16x32_bf16 v[124:127], v[132:135], v[182:185], v[124:127]
	v_mfma_f32_16x16x32_bf16 v[120:123], v[140:143], v[182:185], v[120:123]
	v_mfma_f32_16x16x32_bf16 v[108:111], v[132:135], v[200:203], v[108:111]
	v_mfma_f32_16x16x32_bf16 v[104:107], v[140:143], v[200:203], v[104:107]
	v_mfma_f32_16x16x32_bf16 v[92:95], v[132:135], v[208:211], v[92:95]
	v_mfma_f32_16x16x32_bf16 v[88:91], v[140:143], v[208:211], v[88:91]
	v_mfma_f32_16x16x32_bf16 v[76:79], v[132:135], v[216:219], v[76:79]
	v_mfma_f32_16x16x32_bf16 v[72:75], v[140:143], v[216:219], v[72:75]
	v_mfma_f32_16x16x32_bf16 v[116:119], v[144:147], v[178:181], v[116:119]
	v_mfma_f32_16x16x32_bf16 v[112:115], v[168:171], v[178:181], v[112:115]
	v_mfma_f32_16x16x32_bf16 v[100:103], v[144:147], v[196:199], v[100:103]
	v_mfma_f32_16x16x32_bf16 v[96:99], v[168:171], v[196:199], v[96:99]
	v_mfma_f32_16x16x32_bf16 v[84:87], v[144:147], v[204:207], v[84:87]
	v_mfma_f32_16x16x32_bf16 v[80:83], v[168:171], v[204:207], v[80:83]
	v_mfma_f32_16x16x32_bf16 v[68:71], v[144:147], v[212:215], v[68:71]
	v_mfma_f32_16x16x32_bf16 v[64:67], v[168:171], v[212:215], v[64:67]
	v_mfma_f32_16x16x32_bf16 v[116:119], v[148:151], v[182:185], v[116:119]
	v_mfma_f32_16x16x32_bf16 v[112:115], v[172:175], v[182:185], v[112:115]
	v_mfma_f32_16x16x32_bf16 v[100:103], v[148:151], v[200:203], v[100:103]
	v_mfma_f32_16x16x32_bf16 v[96:99], v[172:175], v[200:203], v[96:99]
	v_mfma_f32_16x16x32_bf16 v[84:87], v[148:151], v[208:211], v[84:87]
	v_mfma_f32_16x16x32_bf16 v[80:83], v[172:175], v[208:211], v[80:83]
	v_mfma_f32_16x16x32_bf16 v[68:71], v[148:151], v[216:219], v[68:71]
	v_mfma_f32_16x16x32_bf16 v[64:67], v[172:175], v[216:219], v[64:67]
	s_setprio 0
	s_barrier
	s_add_i32 s42, s74, s15
	s_mov_b32 m0, s42
	ds_read_b128 v[178:181], v194 offset:49152
	ds_read_b128 v[182:185], v194 offset:50176
	ds_read_b128 v[196:199], v194 offset:51200
	ds_read_b128 v[200:203], v194 offset:52224
	ds_read_b128 v[204:207], v194 offset:53248
	ds_read_b128 v[208:211], v194 offset:54272
	ds_read_b128 v[212:215], v194 offset:55296
	ds_read_b128 v[216:219], v194 offset:56320
	global_load_lds_dwordx4 v154, s[98:99]
	s_add_i32 m0, s42, 0x2000
	s_add_u32 s42, s46, 0x160080
	s_addc_u32 s43, s47, 0
	s_add_i32 s46, s87, s15
	global_load_lds_dwordx4 v158, s[98:99]
	s_mov_b32 m0, s46
	s_nop 0
	global_load_lds_dwordx4 v154, s[42:43]
	s_add_i32 m0, s46, 0x2000
	s_nop 0
	global_load_lds_dwordx4 v158, s[42:43]
	s_mov_b32 m0, s66
	s_nop 0
	global_load_lds_dwordx4 v152, s[100:101]
	s_mov_b32 m0, s67
	s_nop 0
	global_load_lds_dwordx4 v156, s[100:101]
	s_waitcnt vmcnt(8)
	s_waitcnt lgkmcnt(0)
	s_setprio 1
	s_barrier
	v_mfma_f32_16x16x32_bf16 v[60:63], v[128:131], v[178:181], v[60:63]
	v_mfma_f32_16x16x32_bf16 v[56:59], v[136:139], v[178:181], v[56:59]
	v_mfma_f32_16x16x32_bf16 v[44:47], v[128:131], v[196:199], v[44:47]
	v_mfma_f32_16x16x32_bf16 v[40:43], v[136:139], v[196:199], v[40:43]
	v_mfma_f32_16x16x32_bf16 v[28:31], v[128:131], v[204:207], v[28:31]
	v_mfma_f32_16x16x32_bf16 v[24:27], v[136:139], v[204:207], v[24:27]
	v_mfma_f32_16x16x32_bf16 v[12:15], v[128:131], v[212:215], v[12:15]
	v_mfma_f32_16x16x32_bf16 v[8:11], v[136:139], v[212:215], v[8:11]
	v_mfma_f32_16x16x32_bf16 v[60:63], v[132:135], v[182:185], v[60:63]
	v_mfma_f32_16x16x32_bf16 v[56:59], v[140:143], v[182:185], v[56:59]
	v_mfma_f32_16x16x32_bf16 v[44:47], v[132:135], v[200:203], v[44:47]
	v_mfma_f32_16x16x32_bf16 v[40:43], v[140:143], v[200:203], v[40:43]
	v_mfma_f32_16x16x32_bf16 v[28:31], v[132:135], v[208:211], v[28:31]
	v_mfma_f32_16x16x32_bf16 v[24:27], v[140:143], v[208:211], v[24:27]
	v_mfma_f32_16x16x32_bf16 v[12:15], v[132:135], v[216:219], v[12:15]
	v_mfma_f32_16x16x32_bf16 v[8:11], v[140:143], v[216:219], v[8:11]
	v_mfma_f32_16x16x32_bf16 v[52:55], v[144:147], v[178:181], v[52:55]
	v_mfma_f32_16x16x32_bf16 v[48:51], v[168:171], v[178:181], v[48:51]
	v_mfma_f32_16x16x32_bf16 v[36:39], v[144:147], v[196:199], v[36:39]
	v_mfma_f32_16x16x32_bf16 v[32:35], v[168:171], v[196:199], v[32:35]
	v_mfma_f32_16x16x32_bf16 v[20:23], v[144:147], v[204:207], v[20:23]
	v_mfma_f32_16x16x32_bf16 v[16:19], v[168:171], v[204:207], v[16:19]
	v_mfma_f32_16x16x32_bf16 v[4:7], v[144:147], v[212:215], v[4:7]
	v_mfma_f32_16x16x32_bf16 v[0:3], v[168:171], v[212:215], v[0:3]
	v_mfma_f32_16x16x32_bf16 v[52:55], v[148:151], v[182:185], v[52:55]
	v_mfma_f32_16x16x32_bf16 v[48:51], v[172:175], v[182:185], v[48:51]
	v_mfma_f32_16x16x32_bf16 v[36:39], v[148:151], v[200:203], v[36:39]
	v_mfma_f32_16x16x32_bf16 v[32:35], v[172:175], v[200:203], v[32:35]
	v_mfma_f32_16x16x32_bf16 v[20:23], v[148:151], v[208:211], v[20:23]
	v_mfma_f32_16x16x32_bf16 v[16:19], v[172:175], v[208:211], v[16:19]
	v_mfma_f32_16x16x32_bf16 v[4:7], v[148:151], v[216:219], v[4:7]
	v_mfma_f32_16x16x32_bf16 v[0:3], v[172:175], v[216:219], v[0:3]
	s_setprio 0
	s_barrier
	s_add_i32 s86, s86, 2
	s_add_u32 s16, s16, 0x100
	s_addc_u32 s17, s17, 0
	s_cmpk_gt_u32 s86, 0x55
	s_mov_b64 s[42:43], s[44:45]
	s_cbranch_scc0 .LBB0_231
	s_branch .Lsapad0
	s_nop 0
	s_nop 0
	s_nop 0
	s_nop 0
	s_nop 0
	s_nop 0
	s_nop 0
	s_nop 0
	s_nop 0
	s_nop 0
	s_nop 0
	s_nop 0
	s_nop 0
	s_nop 0
	s_nop 0
	s_nop 0
	s_nop 0
	s_nop 0
	s_nop 0
	s_nop 0
	s_nop 0
	s_nop 0
	s_nop 0
	s_nop 0
	s_nop 0
	s_nop 0
	s_nop 0
	s_nop 0
	s_nop 0
	s_nop 0
	s_nop 0
	s_nop 0
	s_nop 0
	s_nop 0
	s_nop 0
	s_nop 0

; #define PG8_STAGE(bufoff, gbase, voff) do { _Pragma("unroll") for (int _i = 0; _i < 2; ++_i) \
;         __builtin_amdgcn_global_load_lds((const unsigned*)((const char*)(gbase) + (voff)[_i]), (LAS unsigned*)(lds + (bufoff) + ldsw + _i * 8192), 16, 0, 0); } while (0)
; #define PG8_LDA(dst, b, h) do { _Pragma("unroll") for (int m = 0; m < 4; ++m) _Pragma("unroll") for (int k = 0; k < 2; ++k) dst[m][k] = *(const LAS bf16x8*)(lds + PG8_SA(b, h) + aoff + m * 2048 + k * 1024); } while (0)
; #define PG8_LDB(dst, b, h) do { _Pragma("unroll") for (int n = 0; n < 2; ++n) _Pragma("unroll") for (int k = 0; k < 2; ++k) dst[n][k] = *(const LAS bf16x8*)(lds + PG8_SB(b, h) + boff + n * 2048 + k * 1024); } while (0)
; #define PG8_MMA(ai, bj, At, Bt) do { __builtin_amdgcn_s_setprio(1); _Pragma("unroll") for (int m = 0; m < 4; ++m) _Pragma("unroll") for (int n = 0; n < 2; ++n) _Pragma("unroll") for (int k = 0; k < 2; ++k) \
;         acc[ai][bj][m][n] = __builtin_amdgcn_mfma_f32_16x16x32_bf16(Bt[n][k], At[m][k], acc[ai][bj][m][n], 0, 0, 0); __builtin_amdgcn_s_setprio(0); } while (0)
; #define PG8_WAIT_V(n) asm volatile("s_waitcnt vmcnt(" #n ")" ::: "memory")
; #define PG8_WAIT_L(n) asm volatile("s_waitcnt lgkmcnt(" #n ")" ::: "memory")
; #define PG8_BAR __builtin_amdgcn_s_barrier()
; #define PG8_SCHED __builtin_amdgcn_sched_barrier(0)
; template <class Epi, class Sched, bool ALIGN_EPI = false, bool SP2 = false>
; __device__ __forceinline__ void gemm_phase(LAS unsigned char* lds, const Gemm g, const Sched& S, const Epi& E) {
;     ...
;             if constexpr (SP2) {
;             PG8_LDB(B0, 0, 0); PG8_LDB(B1, 0, 1); PG8_SCHED; PG8_LDA(At, 0, 0); PG8_STAGE(PG8_SA(1, 1), a1 + hstep, voffA);
;             PG8_WAIT_V(8); PG8_WAIT_L(0); PG8_BAR; PG8_MMA(0, 0, At, B0); PG8_MMA(0, 1, At, B1); PG8_BAR; PG8_SCHED;
;             PG8_LDA(At, 0, 1); PG8_STAGE(PG8_SB(0, 0), b2, voffB); PG8_STAGE(PG8_SB(0, 1), b2 + hstep, voffB); PG8_STAGE(PG8_SA(0, 0), a2, voffA);
;             PG8_WAIT_V(8); PG8_WAIT_L(0); PG8_BAR; PG8_MMA(1, 0, At, B0); PG8_MMA(1, 1, At, B1); PG8_BAR; PG8_SCHED;
.LBB0_317:
	v_add_u32_e32 v50, s91, v165
	ds_read_b128 v[154:157], v50
	ds_read_b128 v[158:161], v50 offset:1024
	ds_read_b128 v[190:193], v50 offset:2048
	ds_read_b128 v[194:197], v50 offset:3072
	v_add_u32_e32 v50, s92, v165
	ds_read_b128 v[198:201], v50
	ds_read_b128 v[202:205], v50 offset:1024
	ds_read_b128 v[206:209], v50 offset:2048
	ds_read_b128 v[210:213], v50 offset:3072
	s_add_u32 s72, s10, 0xfff80080
	s_addc_u32 s73, s11, -1
	s_and_b64 s[70:71], s[70:71], exec
	s_cselect_b32 s73, s51, s73
	s_cselect_b32 s72, s67, s72
	s_cselect_b32 s71, s49, s16
	s_cselect_b32 s70, s96, s97
	s_add_i32 m0, s35, 0xc000
	ds_read_b128 v[214:217], v167
	ds_read_b128 v[218:221], v167 offset:1024
	ds_read_b128 v[222:225], v167 offset:2048
	ds_read_b128 v[226:229], v167 offset:3072
	ds_read_b128 v[230:233], v167 offset:4096
	ds_read_b128 v[234:237], v167 offset:5120
	ds_read_b128 v[238:241], v167 offset:6144
	ds_read_b128 v[242:245], v167 offset:7168
	global_load_lds_dwordx4 v144, s[10:11]
	s_add_i32 m0, s35, 0xe000
	s_nop 0
	global_load_lds_dwordx4 v146, s[10:11]
	s_waitcnt vmcnt(8)
	s_waitcnt lgkmcnt(0)
	s_setprio 1
	s_barrier
	v_mfma_f32_16x16x32_bf16 v[128:131], v[154:157], v[214:217], v[128:131]
	v_mfma_f32_16x16x32_bf16 v[124:127], v[190:193], v[214:217], v[124:127]
	v_mfma_f32_16x16x32_bf16 v[112:115], v[154:157], v[222:225], v[112:115]
	v_mfma_f32_16x16x32_bf16 v[108:111], v[190:193], v[222:225], v[108:111]
	v_mfma_f32_16x16x32_bf16 v[96:99], v[154:157], v[230:233], v[96:99]
	v_mfma_f32_16x16x32_bf16 v[92:95], v[190:193], v[230:233], v[92:95]
	v_mfma_f32_16x16x32_bf16 v[80:83], v[154:157], v[238:241], v[80:83]
	v_mfma_f32_16x16x32_bf16 v[76:79], v[190:193], v[238:241], v[76:79]
	v_mfma_f32_16x16x32_bf16 v[128:131], v[158:161], v[218:221], v[128:131]
	v_mfma_f32_16x16x32_bf16 v[124:127], v[194:197], v[218:221], v[124:127]
	v_mfma_f32_16x16x32_bf16 v[112:115], v[158:161], v[226:229], v[112:115]
	v_mfma_f32_16x16x32_bf16 v[108:111], v[194:197], v[226:229], v[108:111]
	v_mfma_f32_16x16x32_bf16 v[96:99], v[158:161], v[234:237], v[96:99]
	v_mfma_f32_16x16x32_bf16 v[92:95], v[194:197], v[234:237], v[92:95]
	v_mfma_f32_16x16x32_bf16 v[80:83], v[158:161], v[242:245], v[80:83]
	v_mfma_f32_16x16x32_bf16 v[76:79], v[194:197], v[242:245], v[76:79]
	v_mfma_f32_16x16x32_bf16 v[120:123], v[198:201], v[214:217], v[120:123]
	v_mfma_f32_16x16x32_bf16 v[116:119], v[206:209], v[214:217], v[116:119]
	v_mfma_f32_16x16x32_bf16 v[104:107], v[198:201], v[222:225], v[104:107]
	v_mfma_f32_16x16x32_bf16 v[100:103], v[206:209], v[222:225], v[100:103]
	v_mfma_f32_16x16x32_bf16 v[88:91], v[198:201], v[230:233], v[88:91]
	v_mfma_f32_16x16x32_bf16 v[84:87], v[206:209], v[230:233], v[84:87]
	v_mfma_f32_16x16x32_bf16 v[72:75], v[198:201], v[238:241], v[72:75]
	v_mfma_f32_16x16x32_bf16 v[68:71], v[206:209], v[238:241], v[68:71]
	v_mfma_f32_16x16x32_bf16 v[120:123], v[202:205], v[218:221], v[120:123]
	v_mfma_f32_16x16x32_bf16 v[116:119], v[210:213], v[218:221], v[116:119]
	v_mfma_f32_16x16x32_bf16 v[104:107], v[202:205], v[226:229], v[104:107]
	v_mfma_f32_16x16x32_bf16 v[100:103], v[210:213], v[226:229], v[100:103]
	v_mfma_f32_16x16x32_bf16 v[88:91], v[202:205], v[234:237], v[88:91]
	v_mfma_f32_16x16x32_bf16 v[84:87], v[210:213], v[234:237], v[84:87]
	v_mfma_f32_16x16x32_bf16 v[72:75], v[202:205], v[242:245], v[72:75]
	v_mfma_f32_16x16x32_bf16 v[68:71], v[210:213], v[242:245], v[68:71]
	s_setprio 0
	s_barrier
	s_add_u32 s100, s72, 0x80
	s_addc_u32 s101, s73, 0
	s_add_u32 s98, s70, 0x80
	s_addc_u32 s99, s71, 0
	s_add_i32 s74, s91, s15
	s_mov_b32 m0, s74
	ds_read_b128 v[214:217], v167 offset:16384
	ds_read_b128 v[218:221], v167 offset:17408
	ds_read_b128 v[222:225], v167 offset:18432
	ds_read_b128 v[226:229], v167 offset:19456
	ds_read_b128 v[230:233], v167 offset:20480
	ds_read_b128 v[234:237], v167 offset:21504
	ds_read_b128 v[238:241], v167 offset:22528
	ds_read_b128 v[242:245], v167 offset:23552
	global_load_lds_dwordx4 v132, s[70:71]
	s_add_i32 m0, s74, 0x2000
	s_add_u32 vcc_lo, s70, 0x80000
	s_addc_u32 vcc_hi, s71, 0
	s_add_i32 s74, s92, s15
	global_load_lds_dwordx4 v134, s[70:71]
	s_mov_b32 m0, s74
	s_nop 0
	global_load_lds_dwordx4 v132, vcc
	s_add_i32 m0, s74, 0x2000
	s_nop 0
	global_load_lds_dwordx4 v134, vcc
	s_mov_b32 m0, s35
	s_nop 0
	global_load_lds_dwordx4 v132, s[72:73]
	s_mov_b32 m0, s69
	s_nop 0
	global_load_lds_dwordx4 v134, s[72:73]
	s_waitcnt vmcnt(8)
	s_waitcnt lgkmcnt(0)
	s_setprio 1
	s_barrier
	v_mfma_f32_16x16x32_bf16 v[64:67], v[154:157], v[214:217], v[64:67]
	v_mfma_f32_16x16x32_bf16 v[60:63], v[190:193], v[214:217], v[60:63]
	v_mfma_f32_16x16x32_bf16 v[44:47], v[154:157], v[222:225], v[44:47]
	v_mfma_f32_16x16x32_bf16 v[40:43], v[190:193], v[222:225], v[40:43]
	v_mfma_f32_16x16x32_bf16 v[28:31], v[154:157], v[230:233], v[28:31]
	v_mfma_f32_16x16x32_bf16 v[24:27], v[190:193], v[230:233], v[24:27]
	v_mfma_f32_16x16x32_bf16 v[12:15], v[154:157], v[238:241], v[12:15]
	v_mfma_f32_16x16x32_bf16 v[8:11], v[190:193], v[238:241], v[8:11]
	v_mfma_f32_16x16x32_bf16 v[64:67], v[158:161], v[218:221], v[64:67]
	v_mfma_f32_16x16x32_bf16 v[60:63], v[194:197], v[218:221], v[60:63]
	v_mfma_f32_16x16x32_bf16 v[44:47], v[158:161], v[226:229], v[44:47]
	v_mfma_f32_16x16x32_bf16 v[40:43], v[194:197], v[226:229], v[40:43]
	v_mfma_f32_16x16x32_bf16 v[28:31], v[158:161], v[234:237], v[28:31]
	v_mfma_f32_16x16x32_bf16 v[24:27], v[194:197], v[234:237], v[24:27]
	v_mfma_f32_16x16x32_bf16 v[12:15], v[158:161], v[242:245], v[12:15]
	v_mfma_f32_16x16x32_bf16 v[8:11], v[194:197], v[242:245], v[8:11]
	v_mfma_f32_16x16x32_bf16 v[56:59], v[198:201], v[214:217], v[56:59]
	v_mfma_f32_16x16x32_bf16 v[50:53], v[206:209], v[214:217], v[52:55]
	v_mfma_f32_16x16x32_bf16 v[36:39], v[198:201], v[222:225], v[36:39]
	v_mfma_f32_16x16x32_bf16 v[32:35], v[206:209], v[222:225], v[32:35]
	v_mfma_f32_16x16x32_bf16 v[20:23], v[198:201], v[230:233], v[20:23]
	v_mfma_f32_16x16x32_bf16 v[16:19], v[206:209], v[230:233], v[16:19]
	v_mfma_f32_16x16x32_bf16 v[4:7], v[198:201], v[238:241], v[4:7]
	v_mfma_f32_16x16x32_bf16 v[0:3], v[206:209], v[238:241], v[0:3]
	v_mfma_f32_16x16x32_bf16 v[56:59], v[202:205], v[218:221], v[56:59]
	v_mfma_f32_16x16x32_bf16 v[50:53], v[210:213], v[218:221], v[50:53]
	v_mfma_f32_16x16x32_bf16 v[36:39], v[202:205], v[226:229], v[36:39]
	v_mfma_f32_16x16x32_bf16 v[32:35], v[210:213], v[226:229], v[32:35]
	v_mfma_f32_16x16x32_bf16 v[20:23], v[202:205], v[234:237], v[20:23]
	v_mfma_f32_16x16x32_bf16 v[16:19], v[210:213], v[234:237], v[16:19]
	v_mfma_f32_16x16x32_bf16 v[4:7], v[202:205], v[242:245], v[4:7]
	v_mfma_f32_16x16x32_bf16 v[0:3], v[210:213], v[242:245], v[0:3]
	s_setprio 0
	s_barrier
; #define PG8_STAGE(bufoff, gbase, voff) do { _Pragma("unroll") for (int _i = 0; _i < 2; ++_i) \
;         __builtin_amdgcn_global_load_lds((const unsigned*)((const char*)(gbase) + (voff)[_i]), (LAS unsigned*)(lds + (bufoff) + ldsw + _i * 8192), 16, 0, 0); } while (0)
; #define PG8_LDA(dst, b, h) do { _Pragma("unroll") for (int m = 0; m < 4; ++m) _Pragma("unroll") for (int k = 0; k < 2; ++k) dst[m][k] = *(const LAS bf16x8*)(lds + PG8_SA(b, h) + aoff + m * 2048 + k * 1024); } while (0)
; #define PG8_LDB(dst, b, h) do { _Pragma("unroll") for (int n = 0; n < 2; ++n) _Pragma("unroll") for (int k = 0; k < 2; ++k) dst[n][k] = *(const LAS bf16x8*)(lds + PG8_SB(b, h) + boff + n * 2048 + k * 1024); } while (0)
; #define PG8_MMA(ai, bj, At, Bt) do { __builtin_amdgcn_s_setprio(1); _Pragma("unroll") for (int m = 0; m < 4; ++m) _Pragma("unroll") for (int n = 0; n < 2; ++n) _Pragma("unroll") for (int k = 0; k < 2; ++k) \
;         acc[ai][bj][m][n] = __builtin_amdgcn_mfma_f32_16x16x32_bf16(Bt[n][k], At[m][k], acc[ai][bj][m][n], 0, 0, 0); __builtin_amdgcn_s_setprio(0); } while (0)
; #define PG8_WAIT_V(n) asm volatile("s_waitcnt vmcnt(" #n ")" ::: "memory")
; #define PG8_WAIT_L(n) asm volatile("s_waitcnt lgkmcnt(" #n ")" ::: "memory")
; #define PG8_BAR __builtin_amdgcn_s_barrier()
; #define PG8_SCHED __builtin_amdgcn_sched_barrier(0)
; template <class Epi, class Sched, bool ALIGN_EPI = false, bool SP2 = false>
; __device__ __forceinline__ void gemm_phase(LAS unsigned char* lds, const Gemm g, const Sched& S, const Epi& E) {
;     ...
;             PG8_LDB(B0, 1, 0); PG8_LDB(B1, 1, 1); PG8_SCHED; PG8_LDA(At, 1, 0); PG8_STAGE(PG8_SA(0, 1), a2 + hstep, voffA);
;             PG8_WAIT_V(8); PG8_WAIT_L(0); PG8_BAR; PG8_MMA(0, 0, At, B0); PG8_MMA(0, 1, At, B1); PG8_BAR; PG8_SCHED;
;             PG8_LDA(At, 1, 1); PG8_STAGE(PG8_SB(1, 0), b3, voffB); PG8_STAGE(PG8_SB(1, 1), b3 + hstep, voffB); PG8_STAGE(PG8_SA(1, 0), a3, voffA);
;             PG8_WAIT_V(8); PG8_WAIT_L(0); PG8_BAR; PG8_MMA(1, 0, At, B0); PG8_MMA(1, 1, At, B1); PG8_BAR; PG8_SCHED;
	s_add_i32 s74, 0, 0x18000
	v_add_u32_e32 v54, s74, v165
	s_add_i32 vcc_lo, 0, 0x1c000
	ds_read_b128 v[154:157], v54
	ds_read_b128 v[158:161], v54 offset:1024
	ds_read_b128 v[190:193], v54 offset:2048
	ds_read_b128 v[194:197], v54 offset:3072
	v_add_u32_e32 v54, vcc_lo, v165
	ds_read_b128 v[198:201], v54
	ds_read_b128 v[202:205], v54 offset:1024
	ds_read_b128 v[206:209], v54 offset:2048
	ds_read_b128 v[210:213], v54 offset:3072
	s_add_u32 s72, s72, 0x80000
	s_addc_u32 s73, s73, 0
	s_mov_b32 m0, s86
	ds_read_b128 v[214:217], v167 offset:32768
	ds_read_b128 v[218:221], v167 offset:33792
	ds_read_b128 v[222:225], v167 offset:34816
	ds_read_b128 v[226:229], v167 offset:35840
	ds_read_b128 v[230:233], v167 offset:36864
	ds_read_b128 v[234:237], v167 offset:37888
	ds_read_b128 v[238:241], v167 offset:38912
	ds_read_b128 v[242:245], v167 offset:39936
	global_load_lds_dwordx4 v132, s[72:73]
	s_mov_b32 m0, s87
	s_nop 0
	global_load_lds_dwordx4 v134, s[72:73]
	s_waitcnt vmcnt(8)
	s_waitcnt lgkmcnt(0)
	s_setprio 1
	s_barrier
	v_mfma_f32_16x16x32_bf16 v[128:131], v[154:157], v[214:217], v[128:131]
	v_mfma_f32_16x16x32_bf16 v[124:127], v[190:193], v[214:217], v[124:127]
	v_mfma_f32_16x16x32_bf16 v[112:115], v[154:157], v[222:225], v[112:115]
	v_mfma_f32_16x16x32_bf16 v[108:111], v[190:193], v[222:225], v[108:111]
	v_mfma_f32_16x16x32_bf16 v[96:99], v[154:157], v[230:233], v[96:99]
	v_mfma_f32_16x16x32_bf16 v[92:95], v[190:193], v[230:233], v[92:95]
	v_mfma_f32_16x16x32_bf16 v[80:83], v[154:157], v[238:241], v[80:83]
	v_mfma_f32_16x16x32_bf16 v[76:79], v[190:193], v[238:241], v[76:79]
	v_mfma_f32_16x16x32_bf16 v[128:131], v[158:161], v[218:221], v[128:131]
	v_mfma_f32_16x16x32_bf16 v[124:127], v[194:197], v[218:221], v[124:127]
	v_mfma_f32_16x16x32_bf16 v[112:115], v[158:161], v[226:229], v[112:115]
	v_mfma_f32_16x16x32_bf16 v[108:111], v[194:197], v[226:229], v[108:111]
	v_mfma_f32_16x16x32_bf16 v[96:99], v[158:161], v[234:237], v[96:99]
	v_mfma_f32_16x16x32_bf16 v[92:95], v[194:197], v[234:237], v[92:95]
	v_mfma_f32_16x16x32_bf16 v[80:83], v[158:161], v[242:245], v[80:83]
	v_mfma_f32_16x16x32_bf16 v[76:79], v[194:197], v[242:245], v[76:79]
	v_mfma_f32_16x16x32_bf16 v[120:123], v[198:201], v[214:217], v[120:123]
	v_mfma_f32_16x16x32_bf16 v[116:119], v[206:209], v[214:217], v[116:119]
	v_mfma_f32_16x16x32_bf16 v[104:107], v[198:201], v[222:225], v[104:107]
	v_mfma_f32_16x16x32_bf16 v[100:103], v[206:209], v[222:225], v[100:103]
	v_mfma_f32_16x16x32_bf16 v[88:91], v[198:201], v[230:233], v[88:91]
	v_mfma_f32_16x16x32_bf16 v[84:87], v[206:209], v[230:233], v[84:87]
	v_mfma_f32_16x16x32_bf16 v[72:75], v[198:201], v[238:241], v[72:75]
	v_mfma_f32_16x16x32_bf16 v[68:71], v[206:209], v[238:241], v[68:71]
	v_mfma_f32_16x16x32_bf16 v[120:123], v[202:205], v[218:221], v[120:123]
	v_mfma_f32_16x16x32_bf16 v[116:119], v[210:213], v[218:221], v[116:119]
	v_mfma_f32_16x16x32_bf16 v[104:107], v[202:205], v[226:229], v[104:107]
	v_mfma_f32_16x16x32_bf16 v[100:103], v[210:213], v[226:229], v[100:103]
	v_mfma_f32_16x16x32_bf16 v[88:91], v[202:205], v[234:237], v[88:91]
	v_mfma_f32_16x16x32_bf16 v[84:87], v[210:213], v[234:237], v[84:87]
	v_mfma_f32_16x16x32_bf16 v[72:75], v[202:205], v[242:245], v[72:75]
	v_mfma_f32_16x16x32_bf16 v[68:71], v[210:213], v[242:245], v[68:71]
	s_setprio 0
	s_barrier
	s_add_i32 s72, s74, s15
	s_mov_b32 m0, s72
	ds_read_b128 v[214:217], v167 offset:49152
	ds_read_b128 v[218:221], v167 offset:50176
	ds_read_b128 v[222:225], v167 offset:51200
	ds_read_b128 v[226:229], v167 offset:52224
	ds_read_b128 v[230:233], v167 offset:53248
	ds_read_b128 v[234:237], v167 offset:54272
	ds_read_b128 v[238:241], v167 offset:55296
	ds_read_b128 v[242:245], v167 offset:56320
	global_load_lds_dwordx4 v132, s[98:99]
	s_add_i32 m0, s72, 0x2000
	s_add_u32 s70, s70, 0x80080
	s_addc_u32 s71, s71, 0
	s_add_i32 s72, vcc_lo, s15
	global_load_lds_dwordx4 v134, s[98:99]
	s_mov_b32 m0, s72
	s_nop 0
	global_load_lds_dwordx4 v132, s[70:71]
	s_add_i32 m0, s72, 0x2000
	s_nop 0
	global_load_lds_dwordx4 v134, s[70:71]
	s_mov_b32 m0, s89
	s_nop 0
	global_load_lds_dwordx4 v132, s[100:101]
	s_mov_b32 m0, s90
	s_nop 0
	global_load_lds_dwordx4 v134, s[100:101]
	s_waitcnt vmcnt(8)
	s_waitcnt lgkmcnt(0)
	s_setprio 1
	s_barrier
	v_mfma_f32_16x16x32_bf16 v[64:67], v[154:157], v[214:217], v[64:67]
	v_mfma_f32_16x16x32_bf16 v[60:63], v[190:193], v[214:217], v[60:63]
	v_mfma_f32_16x16x32_bf16 v[44:47], v[154:157], v[222:225], v[44:47]
	v_mfma_f32_16x16x32_bf16 v[40:43], v[190:193], v[222:225], v[40:43]
	v_mfma_f32_16x16x32_bf16 v[28:31], v[154:157], v[230:233], v[28:31]
	v_mfma_f32_16x16x32_bf16 v[24:27], v[190:193], v[230:233], v[24:27]
	v_mfma_f32_16x16x32_bf16 v[12:15], v[154:157], v[238:241], v[12:15]
	v_mfma_f32_16x16x32_bf16 v[8:11], v[190:193], v[238:241], v[8:11]
	v_mfma_f32_16x16x32_bf16 v[64:67], v[158:161], v[218:221], v[64:67]
	v_mfma_f32_16x16x32_bf16 v[60:63], v[194:197], v[218:221], v[60:63]
	v_mfma_f32_16x16x32_bf16 v[44:47], v[158:161], v[226:229], v[44:47]
	v_mfma_f32_16x16x32_bf16 v[40:43], v[194:197], v[226:229], v[40:43]
	v_mfma_f32_16x16x32_bf16 v[28:31], v[158:161], v[234:237], v[28:31]
	v_mfma_f32_16x16x32_bf16 v[24:27], v[194:197], v[234:237], v[24:27]
	v_mfma_f32_16x16x32_bf16 v[12:15], v[158:161], v[242:245], v[12:15]
	v_mfma_f32_16x16x32_bf16 v[8:11], v[194:197], v[242:245], v[8:11]
	v_mfma_f32_16x16x32_bf16 v[54:57], v[198:201], v[214:217], v[56:59]
	v_mfma_f32_16x16x32_bf16 v[50:53], v[206:209], v[214:217], v[50:53]
	v_mfma_f32_16x16x32_bf16 v[36:39], v[198:201], v[222:225], v[36:39]
	v_mfma_f32_16x16x32_bf16 v[32:35], v[206:209], v[222:225], v[32:35]
	v_mfma_f32_16x16x32_bf16 v[20:23], v[198:201], v[230:233], v[20:23]
	v_mfma_f32_16x16x32_bf16 v[16:19], v[206:209], v[230:233], v[16:19]
	v_mfma_f32_16x16x32_bf16 v[4:7], v[198:201], v[238:241], v[4:7]
	v_mfma_f32_16x16x32_bf16 v[0:3], v[206:209], v[238:241], v[0:3]
	v_mfma_f32_16x16x32_bf16 v[56:59], v[202:205], v[218:221], v[54:57]
	v_mfma_f32_16x16x32_bf16 v[52:55], v[210:213], v[218:221], v[50:53]
	v_mfma_f32_16x16x32_bf16 v[36:39], v[202:205], v[226:229], v[36:39]
	v_mfma_f32_16x16x32_bf16 v[32:35], v[210:213], v[226:229], v[32:35]
	v_mfma_f32_16x16x32_bf16 v[20:23], v[202:205], v[234:237], v[20:23]
	v_mfma_f32_16x16x32_bf16 v[16:19], v[210:213], v[234:237], v[16:19]
	v_mfma_f32_16x16x32_bf16 v[4:7], v[202:205], v[242:245], v[4:7]
	v_mfma_f32_16x16x32_bf16 v[0:3], v[210:213], v[242:245], v[0:3]
	s_setprio 0
	s_barrier
	s_add_i32 s17, s17, 2
	s_add_u32 s10, s10, 0x100
	s_addc_u32 s11, s11, 0
	s_add_u32 s97, s97, 0x100
	s_addc_u32 s16, s16, 0
	s_cmp_gt_u32 s17, 29
	s_cbranch_scc1 .LBB0_320
;     __device__ __forceinline__ Pre pre(const Unit& u, int wr, int fr) const { return load_rows8(ss, u, wr, fr); }
;     __device__ __forceinline__ Pre pre(const Unit& u, int wr, int fr) const { return load_rows8(ss, u, wr, fr); }
; template <class Epi, class Sched, bool ALIGN_EPI = false, bool SP2 = false>
; __device__ __forceinline__ void gemm_phase(LAS unsigned char* lds, const Gemm g, const Sched& S, const Epi& E) {
;     ...
;             const bool last = (t == nt - 2);
;             const char* a1 = cA + (size_t)(t + 1) * kstep;
;             const char* a2 = last ? nA : cA + (size_t)(t + 2) * kstep; const char* b2 = last ? nB : cB + (size_t)(t + 2) * kstep;
;             const char* a3 = a2 + kstep; const char* b3 = b2 + kstep;
;             if (last && has_next) { S.a_ready(nxt); pre_nxt = E.pre(nxt, wr, fr); }
; __device__ __forceinline__ PreRows load_rows8(const float* ss, const Unit& u, int wr, int fr) {
;     PreRows p; const float* b = ss + u.pm * BM + wr * 64 + fr;
; #pragma unroll
;     for (int ai = 0; ai < 2; ++ai)
; #pragma unroll
;         for (int m = 0; m < 4; ++m) p.v[ai * 4 + m] = b[ai * HALF + m * 16];
;     return p;
.LBB0_318:
	s_cmp_eq_u32 s17, 28
	s_cselect_b64 s[70:71], -1, 0
	s_and_b64 s[72:73], s[8:9], s[70:71]
	s_andn2_b64 vcc, exec, s[72:73]
	s_cbranch_vccnz .LBB0_317
	global_load_dword v171, v[48:49], off
	global_load_dword v172, v[48:49], off offset:64
	global_load_dword v173, v[48:49], off offset:128
	global_load_dword v174, v[48:49], off offset:192
	global_load_dword v175, v[48:49], off offset:512
	global_load_dword v178, v[48:49], off offset:576
	global_load_dword v179, v[48:49], off offset:640
	global_load_dword v180, v[48:49], off offset:704
	s_branch .LBB0_317
	s_nop 0
	s_nop 0
	s_nop 0
	s_nop 0
	s_nop 0
	s_nop 0
	s_nop 0
	s_nop 0
	s_nop 0
	s_nop 0
	s_nop 0
	s_nop 0
	s_nop 0
	s_nop 0
	s_nop 0
	s_nop 0
	s_nop 0
	s_nop 0
	s_nop 0
	s_nop 0
	s_nop 0
	s_nop 0
	s_nop 0
	s_nop 0
	s_nop 0
	s_nop 0
	s_nop 0
	s_nop 0
	s_nop 0
	s_nop 0
	s_nop 0
	s_nop 0
	s_nop 0
	s_nop 0
	s_nop 0
	s_nop 0

; #define PG8_STAGE(bufoff, gbase, voff) do { _Pragma("unroll") for (int _i = 0; _i < 2; ++_i) \
;         __builtin_amdgcn_global_load_lds((const unsigned*)((const char*)(gbase) + (voff)[_i]), (LAS unsigned*)(lds + (bufoff) + ldsw + _i * 8192), 16, 0, 0); } while (0)
; #define PG8_LDA(dst, b, h) do { _Pragma("unroll") for (int m = 0; m < 4; ++m) _Pragma("unroll") for (int k = 0; k < 2; ++k) dst[m][k] = *(const LAS bf16x8*)(lds + PG8_SA(b, h) + aoff + m * 2048 + k * 1024); } while (0)
; #define PG8_LDB(dst, b, h) do { _Pragma("unroll") for (int n = 0; n < 2; ++n) _Pragma("unroll") for (int k = 0; k < 2; ++k) dst[n][k] = *(const LAS bf16x8*)(lds + PG8_SB(b, h) + boff + n * 2048 + k * 1024); } while (0)
; #define PG8_MMA(ai, bj, At, Bt) do { __builtin_amdgcn_s_setprio(1); _Pragma("unroll") for (int m = 0; m < 4; ++m) _Pragma("unroll") for (int n = 0; n < 2; ++n) _Pragma("unroll") for (int k = 0; k < 2; ++k) \
;         acc[ai][bj][m][n] = __builtin_amdgcn_mfma_f32_16x16x32_bf16(Bt[n][k], At[m][k], acc[ai][bj][m][n], 0, 0, 0); __builtin_amdgcn_s_setprio(0); } while (0)
; #define PG8_WAIT_V(n) asm volatile("s_waitcnt vmcnt(" #n ")" ::: "memory")
; #define PG8_WAIT_L(n) asm volatile("s_waitcnt lgkmcnt(" #n ")" ::: "memory")
; #define PG8_BAR __builtin_amdgcn_s_barrier()
; #define PG8_SCHED __builtin_amdgcn_sched_barrier(0)
; template <class Epi, class Sched, bool ALIGN_EPI = false, bool SP2 = false>
; __device__ __forceinline__ void gemm_phase(LAS unsigned char* lds, const Gemm g, const Sched& S, const Epi& E) {
;     ...
;             if constexpr (SP2) {
;             PG8_LDB(B0, 0, 0); PG8_LDB(B1, 0, 1); PG8_SCHED; PG8_LDA(At, 0, 0); PG8_STAGE(PG8_SA(1, 1), a1 + hstep, voffA);
;             PG8_WAIT_V(8); PG8_WAIT_L(0); PG8_BAR; PG8_MMA(0, 0, At, B0); PG8_MMA(0, 1, At, B1); PG8_BAR; PG8_SCHED;
;             PG8_LDA(At, 0, 1); PG8_STAGE(PG8_SB(0, 0), b2, voffB); PG8_STAGE(PG8_SB(0, 1), b2 + hstep, voffB); PG8_STAGE(PG8_SA(0, 0), a2, voffA);
;             PG8_WAIT_V(8); PG8_WAIT_L(0); PG8_BAR; PG8_MMA(1, 0, At, B0); PG8_MMA(1, 1, At, B1); PG8_BAR; PG8_SCHED;
.LBB0_369:
	ds_read_b128 v[144:147], v167
	ds_read_b128 v[148:151], v167 offset:1024
	ds_read_b128 v[152:155], v167 offset:2048
	ds_read_b128 v[156:159], v167 offset:3072
	ds_read_b128 v[160:163], v168
	ds_read_b128 v[172:175], v168 offset:1024
	ds_read_b128 v[178:181], v168 offset:2048
	ds_read_b128 v[182:185], v168 offset:3072
	s_add_u32 s66, s64, 0xfff80080
	s_addc_u32 s67, s65, -1
	s_cmp_eq_u32 s96, 28
	s_cselect_b32 s69, s16, s67
	s_cselect_b32 s68, s17, s66
	s_cselect_b32 s67, s45, s95
	s_cselect_b32 s66, s47, s94
	s_add_i32 m0, s63, 0xc000
	ds_read_b128 v[190:193], v169
	ds_read_b128 v[194:197], v169 offset:1024
	ds_read_b128 v[198:201], v169 offset:2048
	ds_read_b128 v[202:205], v169 offset:3072
	ds_read_b128 v[206:209], v169 offset:4096
	ds_read_b128 v[210:213], v169 offset:5120
	ds_read_b128 v[214:217], v169 offset:6144
	ds_read_b128 v[218:221], v169 offset:7168
	global_load_lds_dwordx4 v136, s[64:65]
	s_add_i32 m0, s63, 0xe000
	s_nop 0
	global_load_lds_dwordx4 v138, s[64:65]
	s_waitcnt vmcnt(8)
	s_waitcnt lgkmcnt(0)
	s_setprio 1
	s_barrier
	v_mfma_f32_16x16x32_bf16 v[124:127], v[144:147], v[190:193], v[124:127]
	v_mfma_f32_16x16x32_bf16 v[120:123], v[152:155], v[190:193], v[120:123]
	v_mfma_f32_16x16x32_bf16 v[116:119], v[144:147], v[198:201], v[116:119]
	v_mfma_f32_16x16x32_bf16 v[112:115], v[152:155], v[198:201], v[112:115]
	v_mfma_f32_16x16x32_bf16 v[108:111], v[144:147], v[206:209], v[108:111]
	v_mfma_f32_16x16x32_bf16 v[100:103], v[152:155], v[206:209], v[100:103]
	v_mfma_f32_16x16x32_bf16 v[80:83], v[144:147], v[214:217], v[80:83]
	v_mfma_f32_16x16x32_bf16 v[72:75], v[152:155], v[214:217], v[72:75]
	v_mfma_f32_16x16x32_bf16 v[124:127], v[148:151], v[194:197], v[124:127]
	v_mfma_f32_16x16x32_bf16 v[120:123], v[156:159], v[194:197], v[120:123]
	v_mfma_f32_16x16x32_bf16 v[116:119], v[148:151], v[202:205], v[116:119]
	v_mfma_f32_16x16x32_bf16 v[112:115], v[156:159], v[202:205], v[112:115]
	v_mfma_f32_16x16x32_bf16 v[108:111], v[148:151], v[210:213], v[108:111]
	v_mfma_f32_16x16x32_bf16 v[100:103], v[156:159], v[210:213], v[100:103]
	v_mfma_f32_16x16x32_bf16 v[80:83], v[148:151], v[218:221], v[80:83]
	v_mfma_f32_16x16x32_bf16 v[72:75], v[156:159], v[218:221], v[72:75]
	v_mfma_f32_16x16x32_bf16 v[104:107], v[160:163], v[190:193], v[104:107]
	v_mfma_f32_16x16x32_bf16 v[96:99], v[178:181], v[190:193], v[96:99]
	v_mfma_f32_16x16x32_bf16 v[92:95], v[160:163], v[198:201], v[92:95]
	v_mfma_f32_16x16x32_bf16 v[88:91], v[178:181], v[198:201], v[88:91]
	v_mfma_f32_16x16x32_bf16 v[84:87], v[160:163], v[206:209], v[84:87]
	v_mfma_f32_16x16x32_bf16 v[76:79], v[178:181], v[206:209], v[76:79]
	v_mfma_f32_16x16x32_bf16 v[68:71], v[160:163], v[214:217], v[68:71]
	v_mfma_f32_16x16x32_bf16 v[64:67], v[178:181], v[214:217], v[64:67]
	v_mfma_f32_16x16x32_bf16 v[104:107], v[172:175], v[194:197], v[104:107]
	v_mfma_f32_16x16x32_bf16 v[96:99], v[182:185], v[194:197], v[96:99]
	v_mfma_f32_16x16x32_bf16 v[92:95], v[172:175], v[202:205], v[92:95]
	v_mfma_f32_16x16x32_bf16 v[88:91], v[182:185], v[202:205], v[88:91]
	v_mfma_f32_16x16x32_bf16 v[84:87], v[172:175], v[210:213], v[84:87]
	v_mfma_f32_16x16x32_bf16 v[76:79], v[182:185], v[210:213], v[76:79]
	v_mfma_f32_16x16x32_bf16 v[68:71], v[172:175], v[218:221], v[68:71]
	v_mfma_f32_16x16x32_bf16 v[64:67], v[182:185], v[218:221], v[64:67]
	s_setprio 0
	s_barrier
	s_add_u32 s100, s68, 0x80
	s_addc_u32 s101, s69, 0
	s_add_u32 s98, s66, 0x80
	s_addc_u32 s99, s67, 0
	s_add_i32 s74, s87, s70
	s_mov_b32 m0, s74
	ds_read_b128 v[190:193], v169 offset:16384
	ds_read_b128 v[194:197], v169 offset:17408
	ds_read_b128 v[198:201], v169 offset:18432
	ds_read_b128 v[202:205], v169 offset:19456
	ds_read_b128 v[206:209], v169 offset:20480
	ds_read_b128 v[210:213], v169 offset:21504
	ds_read_b128 v[214:217], v169 offset:22528
	ds_read_b128 v[218:221], v169 offset:23552
	global_load_lds_dwordx4 v130, s[66:67]
	s_add_i32 m0, s74, 0x2000
	s_add_u32 vcc_lo, s66, 0x80000
	s_addc_u32 vcc_hi, s67, 0
	s_add_i32 s74, s88, s70
	global_load_lds_dwordx4 v134, s[66:67]
	s_mov_b32 m0, s74
	s_nop 0
	global_load_lds_dwordx4 v130, vcc
	s_add_i32 m0, s74, 0x2000
	s_nop 0
	global_load_lds_dwordx4 v134, vcc
	s_mov_b32 m0, s63
	s_nop 0
	global_load_lds_dwordx4 v128, s[68:69]
	s_mov_b32 m0, s71
	s_nop 0
	global_load_lds_dwordx4 v132, s[68:69]
	s_waitcnt vmcnt(8)
	s_waitcnt lgkmcnt(0)
	s_setprio 1
	s_barrier
	v_mfma_f32_16x16x32_bf16 v[60:63], v[144:147], v[190:193], v[60:63]
	v_mfma_f32_16x16x32_bf16 v[56:59], v[152:155], v[190:193], v[56:59]
	v_mfma_f32_16x16x32_bf16 v[48:51], v[144:147], v[198:201], v[48:51]
	v_mfma_f32_16x16x32_bf16 v[40:43], v[152:155], v[198:201], v[40:43]
	v_mfma_f32_16x16x32_bf16 v[32:35], v[144:147], v[206:209], v[32:35]
	v_mfma_f32_16x16x32_bf16 v[24:27], v[152:155], v[206:209], v[24:27]
	v_mfma_f32_16x16x32_bf16 v[16:19], v[144:147], v[214:217], v[16:19]
	v_mfma_f32_16x16x32_bf16 v[8:11], v[152:155], v[214:217], v[8:11]
	v_mfma_f32_16x16x32_bf16 v[60:63], v[148:151], v[194:197], v[60:63]
	v_mfma_f32_16x16x32_bf16 v[56:59], v[156:159], v[194:197], v[56:59]
	v_mfma_f32_16x16x32_bf16 v[48:51], v[148:151], v[202:205], v[48:51]
	v_mfma_f32_16x16x32_bf16 v[40:43], v[156:159], v[202:205], v[40:43]
	v_mfma_f32_16x16x32_bf16 v[32:35], v[148:151], v[210:213], v[32:35]
	v_mfma_f32_16x16x32_bf16 v[24:27], v[156:159], v[210:213], v[24:27]
	v_mfma_f32_16x16x32_bf16 v[16:19], v[148:151], v[218:221], v[16:19]
	v_mfma_f32_16x16x32_bf16 v[8:11], v[156:159], v[218:221], v[8:11]
	v_mfma_f32_16x16x32_bf16 v[52:55], v[160:163], v[190:193], v[52:55]
	v_mfma_f32_16x16x32_bf16 v[44:47], v[178:181], v[190:193], v[44:47]
	v_mfma_f32_16x16x32_bf16 v[36:39], v[160:163], v[198:201], v[36:39]
	v_mfma_f32_16x16x32_bf16 v[28:31], v[178:181], v[198:201], v[28:31]
	v_mfma_f32_16x16x32_bf16 v[20:23], v[160:163], v[206:209], v[20:23]
	v_mfma_f32_16x16x32_bf16 v[12:15], v[178:181], v[206:209], v[12:15]
	v_mfma_f32_16x16x32_bf16 v[4:7], v[160:163], v[214:217], v[4:7]
	v_mfma_f32_16x16x32_bf16 v[0:3], v[178:181], v[214:217], v[0:3]
	v_mfma_f32_16x16x32_bf16 v[52:55], v[172:175], v[194:197], v[52:55]
	v_mfma_f32_16x16x32_bf16 v[44:47], v[182:185], v[194:197], v[44:47]
	v_mfma_f32_16x16x32_bf16 v[36:39], v[172:175], v[202:205], v[36:39]
	v_mfma_f32_16x16x32_bf16 v[28:31], v[182:185], v[202:205], v[28:31]
	v_mfma_f32_16x16x32_bf16 v[20:23], v[172:175], v[210:213], v[20:23]
	v_mfma_f32_16x16x32_bf16 v[12:15], v[182:185], v[210:213], v[12:15]
	v_mfma_f32_16x16x32_bf16 v[4:7], v[172:175], v[218:221], v[4:7]
	v_mfma_f32_16x16x32_bf16 v[0:3], v[182:185], v[218:221], v[0:3]
	s_setprio 0
	s_barrier
; #define PG8_STAGE(bufoff, gbase, voff) do { _Pragma("unroll") for (int _i = 0; _i < 2; ++_i) \
;         __builtin_amdgcn_global_load_lds((const unsigned*)((const char*)(gbase) + (voff)[_i]), (LAS unsigned*)(lds + (bufoff) + ldsw + _i * 8192), 16, 0, 0); } while (0)
; #define PG8_LDA(dst, b, h) do { _Pragma("unroll") for (int m = 0; m < 4; ++m) _Pragma("unroll") for (int k = 0; k < 2; ++k) dst[m][k] = *(const LAS bf16x8*)(lds + PG8_SA(b, h) + aoff + m * 2048 + k * 1024); } while (0)
; #define PG8_LDB(dst, b, h) do { _Pragma("unroll") for (int n = 0; n < 2; ++n) _Pragma("unroll") for (int k = 0; k < 2; ++k) dst[n][k] = *(const LAS bf16x8*)(lds + PG8_SB(b, h) + boff + n * 2048 + k * 1024); } while (0)
; #define PG8_MMA(ai, bj, At, Bt) do { __builtin_amdgcn_s_setprio(1); _Pragma("unroll") for (int m = 0; m < 4; ++m) _Pragma("unroll") for (int n = 0; n < 2; ++n) _Pragma("unroll") for (int k = 0; k < 2; ++k) \
;         acc[ai][bj][m][n] = __builtin_amdgcn_mfma_f32_16x16x32_bf16(Bt[n][k], At[m][k], acc[ai][bj][m][n], 0, 0, 0); __builtin_amdgcn_s_setprio(0); } while (0)
; #define PG8_WAIT_V(n) asm volatile("s_waitcnt vmcnt(" #n ")" ::: "memory")
; #define PG8_WAIT_L(n) asm volatile("s_waitcnt lgkmcnt(" #n ")" ::: "memory")
; #define PG8_BAR __builtin_amdgcn_s_barrier()
; #define PG8_SCHED __builtin_amdgcn_sched_barrier(0)
; template <class Epi, class Sched, bool ALIGN_EPI = false, bool SP2 = false>
; __device__ __forceinline__ void gemm_phase(LAS unsigned char* lds, const Gemm g, const Sched& S, const Epi& E) {
;     ...
;         for (int t = 0; t < nt; t += 2) {
;             const bool last = (t == nt - 2);
;             const char* a1 = cA + (size_t)(t + 1) * kstep;
;             const char* a2 = last ? nA : cA + (size_t)(t + 2) * kstep; const char* b2 = last ? nB : cB + (size_t)(t + 2) * kstep;
;     ...
;             PG8_LDB(B0, 1, 0); PG8_LDB(B1, 1, 1); PG8_SCHED; PG8_LDA(At, 1, 0); PG8_STAGE(PG8_SA(0, 1), a2 + hstep, voffA);
;             PG8_WAIT_V(8); PG8_WAIT_L(0); PG8_BAR; PG8_MMA(0, 0, At, B0); PG8_MMA(0, 1, At, B1); PG8_BAR; PG8_SCHED;
;             PG8_LDA(At, 1, 1); PG8_STAGE(PG8_SB(1, 0), b3, voffB); PG8_STAGE(PG8_SB(1, 1), b3 + hstep, voffB); PG8_STAGE(PG8_SA(1, 0), a3, voffA);
;             PG8_WAIT_V(8); PG8_WAIT_L(0); PG8_BAR; PG8_MMA(1, 0, At, B0); PG8_MMA(1, 1, At, B1); PG8_BAR; PG8_SCHED;
	s_add_i32 s74, 0, 0x18000
	s_add_i32 s97, 0, 0x1c000
	v_add_u32_e32 v156, s74, v165
	v_add_u32_e32 v171, s97, v165
	ds_read_b128 v[144:147], v156
	ds_read_b128 v[148:151], v156 offset:1024
	ds_read_b128 v[152:155], v156 offset:2048
	ds_read_b128 v[156:159], v156 offset:3072
	ds_read_b128 v[160:163], v171
	ds_read_b128 v[172:175], v171 offset:1024
	ds_read_b128 v[178:181], v171 offset:2048
	ds_read_b128 v[182:185], v171 offset:3072
	s_add_u32 s68, s68, 0x80000
	s_addc_u32 s69, s69, 0
	s_mov_b32 m0, s72
	ds_read_b128 v[190:193], v169 offset:32768
	ds_read_b128 v[194:197], v169 offset:33792
	ds_read_b128 v[198:201], v169 offset:34816
	ds_read_b128 v[202:205], v169 offset:35840
	ds_read_b128 v[206:209], v169 offset:36864
	ds_read_b128 v[210:213], v169 offset:37888
	ds_read_b128 v[214:217], v169 offset:38912
	ds_read_b128 v[218:221], v169 offset:39936
	global_load_lds_dwordx4 v128, s[68:69]
	s_mov_b32 m0, s73
	s_nop 0
	global_load_lds_dwordx4 v132, s[68:69]
	s_waitcnt vmcnt(8)
	s_waitcnt lgkmcnt(0)
	s_setprio 1
	s_barrier
	v_mfma_f32_16x16x32_bf16 v[124:127], v[144:147], v[190:193], v[124:127]
	v_mfma_f32_16x16x32_bf16 v[120:123], v[152:155], v[190:193], v[120:123]
	v_mfma_f32_16x16x32_bf16 v[116:119], v[144:147], v[198:201], v[116:119]
	v_mfma_f32_16x16x32_bf16 v[112:115], v[152:155], v[198:201], v[112:115]
	v_mfma_f32_16x16x32_bf16 v[108:111], v[144:147], v[206:209], v[108:111]
	v_mfma_f32_16x16x32_bf16 v[100:103], v[152:155], v[206:209], v[100:103]
	v_mfma_f32_16x16x32_bf16 v[80:83], v[144:147], v[214:217], v[80:83]
	v_mfma_f32_16x16x32_bf16 v[72:75], v[152:155], v[214:217], v[72:75]
	v_mfma_f32_16x16x32_bf16 v[124:127], v[148:151], v[194:197], v[124:127]
	v_mfma_f32_16x16x32_bf16 v[120:123], v[156:159], v[194:197], v[120:123]
	v_mfma_f32_16x16x32_bf16 v[116:119], v[148:151], v[202:205], v[116:119]
	v_mfma_f32_16x16x32_bf16 v[112:115], v[156:159], v[202:205], v[112:115]
	v_mfma_f32_16x16x32_bf16 v[108:111], v[148:151], v[210:213], v[108:111]
	v_mfma_f32_16x16x32_bf16 v[100:103], v[156:159], v[210:213], v[100:103]
	v_mfma_f32_16x16x32_bf16 v[80:83], v[148:151], v[218:221], v[80:83]
	v_mfma_f32_16x16x32_bf16 v[72:75], v[156:159], v[218:221], v[72:75]
	v_mfma_f32_16x16x32_bf16 v[104:107], v[160:163], v[190:193], v[104:107]
	v_mfma_f32_16x16x32_bf16 v[96:99], v[178:181], v[190:193], v[96:99]
	v_mfma_f32_16x16x32_bf16 v[92:95], v[160:163], v[198:201], v[92:95]
	v_mfma_f32_16x16x32_bf16 v[88:91], v[178:181], v[198:201], v[88:91]
	v_mfma_f32_16x16x32_bf16 v[84:87], v[160:163], v[206:209], v[84:87]
	v_mfma_f32_16x16x32_bf16 v[76:79], v[178:181], v[206:209], v[76:79]
	v_mfma_f32_16x16x32_bf16 v[68:71], v[160:163], v[214:217], v[68:71]
	v_mfma_f32_16x16x32_bf16 v[64:67], v[178:181], v[214:217], v[64:67]
	v_mfma_f32_16x16x32_bf16 v[104:107], v[172:175], v[194:197], v[104:107]
	v_mfma_f32_16x16x32_bf16 v[96:99], v[182:185], v[194:197], v[96:99]
	v_mfma_f32_16x16x32_bf16 v[92:95], v[172:175], v[202:205], v[92:95]
	v_mfma_f32_16x16x32_bf16 v[88:91], v[182:185], v[202:205], v[88:91]
	v_mfma_f32_16x16x32_bf16 v[84:87], v[172:175], v[210:213], v[84:87]
	v_mfma_f32_16x16x32_bf16 v[76:79], v[182:185], v[210:213], v[76:79]
	v_mfma_f32_16x16x32_bf16 v[68:71], v[172:175], v[218:221], v[68:71]
	v_mfma_f32_16x16x32_bf16 v[64:67], v[182:185], v[218:221], v[64:67]
	s_setprio 0
	s_barrier
	s_add_i32 s68, s74, s70
	s_mov_b32 m0, s68
	ds_read_b128 v[190:193], v169 offset:49152
	ds_read_b128 v[194:197], v169 offset:50176
	ds_read_b128 v[198:201], v169 offset:51200
	ds_read_b128 v[202:205], v169 offset:52224
	ds_read_b128 v[206:209], v169 offset:53248
	ds_read_b128 v[210:213], v169 offset:54272
	ds_read_b128 v[214:217], v169 offset:55296
	ds_read_b128 v[218:221], v169 offset:56320
	global_load_lds_dwordx4 v130, s[98:99]
	s_add_i32 m0, s68, 0x2000
	s_add_u32 s66, s66, 0x80080
	s_addc_u32 s67, s67, 0
	s_add_i32 s68, s97, s70
	global_load_lds_dwordx4 v134, s[98:99]
	s_mov_b32 m0, s68
	s_nop 0
	global_load_lds_dwordx4 v130, s[66:67]
	s_add_i32 m0, s68, 0x2000
	s_nop 0
	global_load_lds_dwordx4 v134, s[66:67]
	s_mov_b32 m0, s85
	s_nop 0
	global_load_lds_dwordx4 v128, s[100:101]
	s_mov_b32 m0, s86
	s_nop 0
	global_load_lds_dwordx4 v132, s[100:101]
	s_waitcnt vmcnt(8)
	s_waitcnt lgkmcnt(0)
	s_setprio 1
	s_barrier
	v_mfma_f32_16x16x32_bf16 v[60:63], v[144:147], v[190:193], v[60:63]
	v_mfma_f32_16x16x32_bf16 v[56:59], v[152:155], v[190:193], v[56:59]
	v_mfma_f32_16x16x32_bf16 v[48:51], v[144:147], v[198:201], v[48:51]
	v_mfma_f32_16x16x32_bf16 v[40:43], v[152:155], v[198:201], v[40:43]
	v_mfma_f32_16x16x32_bf16 v[32:35], v[144:147], v[206:209], v[32:35]
	v_mfma_f32_16x16x32_bf16 v[24:27], v[152:155], v[206:209], v[24:27]
	v_mfma_f32_16x16x32_bf16 v[16:19], v[144:147], v[214:217], v[16:19]
	v_mfma_f32_16x16x32_bf16 v[8:11], v[152:155], v[214:217], v[8:11]
	v_mfma_f32_16x16x32_bf16 v[60:63], v[148:151], v[194:197], v[60:63]
	v_mfma_f32_16x16x32_bf16 v[56:59], v[156:159], v[194:197], v[56:59]
	v_mfma_f32_16x16x32_bf16 v[48:51], v[148:151], v[202:205], v[48:51]
	v_mfma_f32_16x16x32_bf16 v[40:43], v[156:159], v[202:205], v[40:43]
	v_mfma_f32_16x16x32_bf16 v[32:35], v[148:151], v[210:213], v[32:35]
	v_mfma_f32_16x16x32_bf16 v[24:27], v[156:159], v[210:213], v[24:27]
	v_mfma_f32_16x16x32_bf16 v[16:19], v[148:151], v[218:221], v[16:19]
	v_mfma_f32_16x16x32_bf16 v[8:11], v[156:159], v[218:221], v[8:11]
	v_mfma_f32_16x16x32_bf16 v[52:55], v[160:163], v[190:193], v[52:55]
	v_mfma_f32_16x16x32_bf16 v[44:47], v[178:181], v[190:193], v[44:47]
	v_mfma_f32_16x16x32_bf16 v[36:39], v[160:163], v[198:201], v[36:39]
	v_mfma_f32_16x16x32_bf16 v[28:31], v[178:181], v[198:201], v[28:31]
	v_mfma_f32_16x16x32_bf16 v[20:23], v[160:163], v[206:209], v[20:23]
	v_mfma_f32_16x16x32_bf16 v[12:15], v[178:181], v[206:209], v[12:15]
	v_mfma_f32_16x16x32_bf16 v[4:7], v[160:163], v[214:217], v[4:7]
	v_mfma_f32_16x16x32_bf16 v[0:3], v[178:181], v[214:217], v[0:3]
	v_mfma_f32_16x16x32_bf16 v[52:55], v[172:175], v[194:197], v[52:55]
	v_mfma_f32_16x16x32_bf16 v[44:47], v[182:185], v[194:197], v[44:47]
	v_mfma_f32_16x16x32_bf16 v[36:39], v[172:175], v[202:205], v[36:39]
	v_mfma_f32_16x16x32_bf16 v[28:31], v[182:185], v[202:205], v[28:31]
	v_mfma_f32_16x16x32_bf16 v[20:23], v[172:175], v[210:213], v[20:23]
	v_mfma_f32_16x16x32_bf16 v[12:15], v[182:185], v[210:213], v[12:15]
	v_mfma_f32_16x16x32_bf16 v[4:7], v[172:175], v[218:221], v[4:7]
	v_mfma_f32_16x16x32_bf16 v[0:3], v[182:185], v[218:221], v[0:3]
	s_setprio 0
	s_barrier
	s_add_i32 s96, s96, 2
	s_add_u32 s64, s64, 0x100
	s_addc_u32 s65, s65, 0
	s_add_u32 s94, s94, 0x100
	s_addc_u32 s95, s95, 0
	s_cmp_gt_u32 s96, 29
	s_cbranch_scc0 .LBB0_369
	s_branch .Lsapad1
	s_nop 0
	s_nop 0
	s_nop 0
	s_nop 0
	s_nop 0
	s_nop 0
	s_nop 0
	s_nop 0
	s_nop 0
	s_nop 0
	s_nop 0
	s_nop 0
	s_nop 0
	s_nop 0
	s_nop 0
	s_nop 0
	s_nop 0
	s_nop 0
	s_nop 0
	s_nop 0
	s_nop 0
	s_nop 0
	s_nop 0
	s_nop 0
	s_nop 0
	s_nop 0
	s_nop 0
	s_nop 0
	s_nop 0
	s_nop 0
	s_nop 0
	s_nop 0
	s_nop 0
	s_nop 0
	s_nop 0
	s_nop 0

; #define PG8_STAGE(bufoff, gbase, voff) do { _Pragma("unroll") for (int _i = 0; _i < 2; ++_i) \
;         __builtin_amdgcn_global_load_lds((const unsigned*)((const char*)(gbase) + (voff)[_i]), (LAS unsigned*)(lds + (bufoff) + ldsw + _i * 8192), 16, 0, 0); } while (0)
; #define PG8_LDA(dst, b, h) do { _Pragma("unroll") for (int m = 0; m < 4; ++m) _Pragma("unroll") for (int k = 0; k < 2; ++k) dst[m][k] = *(const LAS bf16x8*)(lds + PG8_SA(b, h) + aoff + m * 2048 + k * 1024); } while (0)
; #define PG8_LDB(dst, b, h) do { _Pragma("unroll") for (int n = 0; n < 2; ++n) _Pragma("unroll") for (int k = 0; k < 2; ++k) dst[n][k] = *(const LAS bf16x8*)(lds + PG8_SB(b, h) + boff + n * 2048 + k * 1024); } while (0)
; #define PG8_MMA(ai, bj, At, Bt) do { __builtin_amdgcn_s_setprio(1); _Pragma("unroll") for (int m = 0; m < 4; ++m) _Pragma("unroll") for (int n = 0; n < 2; ++n) _Pragma("unroll") for (int k = 0; k < 2; ++k) \
;         acc[ai][bj][m][n] = __builtin_amdgcn_mfma_f32_16x16x32_bf16(Bt[n][k], At[m][k], acc[ai][bj][m][n], 0, 0, 0); __builtin_amdgcn_s_setprio(0); } while (0)
; #define PG8_WAIT_V(n) asm volatile("s_waitcnt vmcnt(" #n ")" ::: "memory")
; #define PG8_WAIT_L(n) asm volatile("s_waitcnt lgkmcnt(" #n ")" ::: "memory")
; #define PG8_BAR __builtin_amdgcn_s_barrier()
; #define PG8_SCHED __builtin_amdgcn_sched_barrier(0)
; template <class Epi, class Sched, bool ALIGN_EPI = false, bool SP2 = false>
; __device__ __forceinline__ void gemm_phase(LAS unsigned char* lds, const Gemm g, const Sched& S, const Epi& E) {
;     ...
;             if constexpr (SP2) {
;             PG8_LDB(B0, 0, 0); PG8_LDB(B1, 0, 1); PG8_SCHED; PG8_LDA(At, 0, 0); PG8_STAGE(PG8_SA(1, 1), a1 + hstep, voffA);
;             PG8_WAIT_V(8); PG8_WAIT_L(0); PG8_BAR; PG8_MMA(0, 0, At, B0); PG8_MMA(0, 1, At, B1); PG8_BAR; PG8_SCHED;
;             PG8_LDA(At, 0, 1); PG8_STAGE(PG8_SB(0, 0), b2, voffB); PG8_STAGE(PG8_SB(0, 1), b2 + hstep, voffB); PG8_STAGE(PG8_SA(0, 0), a2, voffA);
;             PG8_WAIT_V(8); PG8_WAIT_L(0); PG8_BAR; PG8_MMA(1, 0, At, B0); PG8_MMA(1, 1, At, B1); PG8_BAR; PG8_SCHED;
.LBB0_626:
	ds_read_b128 v[128:131], v192
	ds_read_b128 v[132:135], v192 offset:1024
	ds_read_b128 v[136:139], v192 offset:2048
	ds_read_b128 v[140:143], v192 offset:3072
	ds_read_b128 v[144:147], v193
	ds_read_b128 v[148:151], v193 offset:1024
	ds_read_b128 v[168:171], v193 offset:2048
	ds_read_b128 v[172:175], v193 offset:3072
	s_add_u32 s58, s50, 0xfff80080
	s_addc_u32 s59, s51, -1
	s_cmp_eq_u32 s70, 28
	s_cselect_b32 s61, s16, s59
	s_cselect_b32 s60, s17, s58
	s_cselect_b32 s59, s39, s69
	s_cselect_b32 s58, s41, s47
	s_add_i32 m0, s35, 0xc000
	ds_read_b128 v[178:181], v194
	ds_read_b128 v[182:185], v194 offset:1024
	ds_read_b128 v[196:199], v194 offset:2048
	ds_read_b128 v[200:203], v194 offset:3072
	ds_read_b128 v[204:207], v194 offset:4096
	ds_read_b128 v[208:211], v194 offset:5120
	ds_read_b128 v[212:215], v194 offset:6144
	ds_read_b128 v[216:219], v194 offset:7168
	global_load_lds_dwordx4 v160, s[50:51]
	s_add_i32 m0, s35, 0xe000
	s_nop 0
	global_load_lds_dwordx4 v162, s[50:51]
	s_waitcnt vmcnt(8)
	s_waitcnt lgkmcnt(0)
	s_setprio 1
	s_barrier
	v_mfma_f32_16x16x32_bf16 v[124:127], v[128:131], v[178:181], v[124:127]
	v_mfma_f32_16x16x32_bf16 v[120:123], v[136:139], v[178:181], v[120:123]
	v_mfma_f32_16x16x32_bf16 v[108:111], v[128:131], v[196:199], v[108:111]
	v_mfma_f32_16x16x32_bf16 v[104:107], v[136:139], v[196:199], v[104:107]
	v_mfma_f32_16x16x32_bf16 v[92:95], v[128:131], v[204:207], v[92:95]
	v_mfma_f32_16x16x32_bf16 v[88:91], v[136:139], v[204:207], v[88:91]
	v_mfma_f32_16x16x32_bf16 v[76:79], v[128:131], v[212:215], v[76:79]
	v_mfma_f32_16x16x32_bf16 v[72:75], v[136:139], v[212:215], v[72:75]
	v_mfma_f32_16x16x32_bf16 v[124:127], v[132:135], v[182:185], v[124:127]
	v_mfma_f32_16x16x32_bf16 v[120:123], v[140:143], v[182:185], v[120:123]
	v_mfma_f32_16x16x32_bf16 v[108:111], v[132:135], v[200:203], v[108:111]
	v_mfma_f32_16x16x32_bf16 v[104:107], v[140:143], v[200:203], v[104:107]
	v_mfma_f32_16x16x32_bf16 v[92:95], v[132:135], v[208:211], v[92:95]
	v_mfma_f32_16x16x32_bf16 v[88:91], v[140:143], v[208:211], v[88:91]
	v_mfma_f32_16x16x32_bf16 v[76:79], v[132:135], v[216:219], v[76:79]
	v_mfma_f32_16x16x32_bf16 v[72:75], v[140:143], v[216:219], v[72:75]
	v_mfma_f32_16x16x32_bf16 v[116:119], v[144:147], v[178:181], v[116:119]
	v_mfma_f32_16x16x32_bf16 v[112:115], v[168:171], v[178:181], v[112:115]
	v_mfma_f32_16x16x32_bf16 v[100:103], v[144:147], v[196:199], v[100:103]
	v_mfma_f32_16x16x32_bf16 v[96:99], v[168:171], v[196:199], v[96:99]
	v_mfma_f32_16x16x32_bf16 v[84:87], v[144:147], v[204:207], v[84:87]
	v_mfma_f32_16x16x32_bf16 v[80:83], v[168:171], v[204:207], v[80:83]
	v_mfma_f32_16x16x32_bf16 v[68:71], v[144:147], v[212:215], v[68:71]
	v_mfma_f32_16x16x32_bf16 v[64:67], v[168:171], v[212:215], v[64:67]
	v_mfma_f32_16x16x32_bf16 v[116:119], v[148:151], v[182:185], v[116:119]
	v_mfma_f32_16x16x32_bf16 v[112:115], v[172:175], v[182:185], v[112:115]
	v_mfma_f32_16x16x32_bf16 v[100:103], v[148:151], v[200:203], v[100:103]
	v_mfma_f32_16x16x32_bf16 v[96:99], v[172:175], v[200:203], v[96:99]
	v_mfma_f32_16x16x32_bf16 v[84:87], v[148:151], v[208:211], v[84:87]
	v_mfma_f32_16x16x32_bf16 v[80:83], v[172:175], v[208:211], v[80:83]
	v_mfma_f32_16x16x32_bf16 v[68:71], v[148:151], v[216:219], v[68:71]
	v_mfma_f32_16x16x32_bf16 v[64:67], v[172:175], v[216:219], v[64:67]
	s_setprio 0
	s_barrier
	s_add_u32 s100, s60, 0x80
	s_addc_u32 s101, s61, 0
	s_add_u32 s98, s58, 0x80
	s_addc_u32 s99, s59, 0
	s_add_i32 s71, s67, s15
	s_mov_b32 m0, s71
	ds_read_b128 v[178:181], v194 offset:16384
	ds_read_b128 v[182:185], v194 offset:17408
	ds_read_b128 v[196:199], v194 offset:18432
	ds_read_b128 v[200:203], v194 offset:19456
	ds_read_b128 v[204:207], v194 offset:20480
	ds_read_b128 v[208:211], v194 offset:21504
	ds_read_b128 v[212:215], v194 offset:22528
	ds_read_b128 v[216:219], v194 offset:23552
	global_load_lds_dwordx4 v154, s[58:59]
	s_add_i32 m0, s71, 0x2000
	s_add_u32 s72, s58, 0x80000
	s_addc_u32 s73, s59, 0
	s_add_i32 s71, s68, s15
	global_load_lds_dwordx4 v158, s[58:59]
	s_mov_b32 m0, s71
	s_nop 0
	global_load_lds_dwordx4 v154, s[72:73]
	s_add_i32 m0, s71, 0x2000
	s_nop 0
	global_load_lds_dwordx4 v158, s[72:73]
	s_mov_b32 m0, s35
	s_nop 0
	global_load_lds_dwordx4 v152, s[60:61]
	s_mov_b32 m0, s49
	s_nop 0
	global_load_lds_dwordx4 v156, s[60:61]
	s_waitcnt vmcnt(8)
	s_waitcnt lgkmcnt(0)
	s_setprio 1
	s_barrier
	v_mfma_f32_16x16x32_bf16 v[60:63], v[128:131], v[178:181], v[60:63]
	v_mfma_f32_16x16x32_bf16 v[56:59], v[136:139], v[178:181], v[56:59]
	v_mfma_f32_16x16x32_bf16 v[44:47], v[128:131], v[196:199], v[44:47]
	v_mfma_f32_16x16x32_bf16 v[40:43], v[136:139], v[196:199], v[40:43]
	v_mfma_f32_16x16x32_bf16 v[28:31], v[128:131], v[204:207], v[28:31]
	v_mfma_f32_16x16x32_bf16 v[24:27], v[136:139], v[204:207], v[24:27]
	v_mfma_f32_16x16x32_bf16 v[12:15], v[128:131], v[212:215], v[12:15]
	v_mfma_f32_16x16x32_bf16 v[8:11], v[136:139], v[212:215], v[8:11]
	v_mfma_f32_16x16x32_bf16 v[60:63], v[132:135], v[182:185], v[60:63]
	v_mfma_f32_16x16x32_bf16 v[56:59], v[140:143], v[182:185], v[56:59]
	v_mfma_f32_16x16x32_bf16 v[44:47], v[132:135], v[200:203], v[44:47]
	v_mfma_f32_16x16x32_bf16 v[40:43], v[140:143], v[200:203], v[40:43]
	v_mfma_f32_16x16x32_bf16 v[28:31], v[132:135], v[208:211], v[28:31]
	v_mfma_f32_16x16x32_bf16 v[24:27], v[140:143], v[208:211], v[24:27]
	v_mfma_f32_16x16x32_bf16 v[12:15], v[132:135], v[216:219], v[12:15]
	v_mfma_f32_16x16x32_bf16 v[8:11], v[140:143], v[216:219], v[8:11]
	v_mfma_f32_16x16x32_bf16 v[52:55], v[144:147], v[178:181], v[52:55]
	v_mfma_f32_16x16x32_bf16 v[48:51], v[168:171], v[178:181], v[48:51]
	v_mfma_f32_16x16x32_bf16 v[36:39], v[144:147], v[196:199], v[36:39]
	v_mfma_f32_16x16x32_bf16 v[32:35], v[168:171], v[196:199], v[32:35]
	v_mfma_f32_16x16x32_bf16 v[20:23], v[144:147], v[204:207], v[20:23]
	v_mfma_f32_16x16x32_bf16 v[16:19], v[168:171], v[204:207], v[16:19]
	v_mfma_f32_16x16x32_bf16 v[4:7], v[144:147], v[212:215], v[4:7]
	v_mfma_f32_16x16x32_bf16 v[0:3], v[168:171], v[212:215], v[0:3]
	v_mfma_f32_16x16x32_bf16 v[52:55], v[148:151], v[182:185], v[52:55]
	v_mfma_f32_16x16x32_bf16 v[48:51], v[172:175], v[182:185], v[48:51]
	v_mfma_f32_16x16x32_bf16 v[36:39], v[148:151], v[200:203], v[36:39]
	v_mfma_f32_16x16x32_bf16 v[32:35], v[172:175], v[200:203], v[32:35]
	v_mfma_f32_16x16x32_bf16 v[20:23], v[148:151], v[208:211], v[20:23]
	v_mfma_f32_16x16x32_bf16 v[16:19], v[172:175], v[208:211], v[16:19]
	v_mfma_f32_16x16x32_bf16 v[4:7], v[148:151], v[216:219], v[4:7]
	v_mfma_f32_16x16x32_bf16 v[0:3], v[172:175], v[216:219], v[0:3]
	s_setprio 0
	s_barrier
; #define PG8_STAGE(bufoff, gbase, voff) do { _Pragma("unroll") for (int _i = 0; _i < 2; ++_i) \
;         __builtin_amdgcn_global_load_lds((const unsigned*)((const char*)(gbase) + (voff)[_i]), (LAS unsigned*)(lds + (bufoff) + ldsw + _i * 8192), 16, 0, 0); } while (0)
; #define PG8_LDA(dst, b, h) do { _Pragma("unroll") for (int m = 0; m < 4; ++m) _Pragma("unroll") for (int k = 0; k < 2; ++k) dst[m][k] = *(const LAS bf16x8*)(lds + PG8_SA(b, h) + aoff + m * 2048 + k * 1024); } while (0)
; #define PG8_LDB(dst, b, h) do { _Pragma("unroll") for (int n = 0; n < 2; ++n) _Pragma("unroll") for (int k = 0; k < 2; ++k) dst[n][k] = *(const LAS bf16x8*)(lds + PG8_SB(b, h) + boff + n * 2048 + k * 1024); } while (0)
; #define PG8_MMA(ai, bj, At, Bt) do { __builtin_amdgcn_s_setprio(1); _Pragma("unroll") for (int m = 0; m < 4; ++m) _Pragma("unroll") for (int n = 0; n < 2; ++n) _Pragma("unroll") for (int k = 0; k < 2; ++k) \
;         acc[ai][bj][m][n] = __builtin_amdgcn_mfma_f32_16x16x32_bf16(Bt[n][k], At[m][k], acc[ai][bj][m][n], 0, 0, 0); __builtin_amdgcn_s_setprio(0); } while (0)
; #define PG8_WAIT_V(n) asm volatile("s_waitcnt vmcnt(" #n ")" ::: "memory")
; #define PG8_WAIT_L(n) asm volatile("s_waitcnt lgkmcnt(" #n ")" ::: "memory")
; #define PG8_BAR __builtin_amdgcn_s_barrier()
; #define PG8_SCHED __builtin_amdgcn_sched_barrier(0)
; template <class Epi, class Sched, bool ALIGN_EPI = false, bool SP2 = false>
; __device__ __forceinline__ void gemm_phase(LAS unsigned char* lds, const Gemm g, const Sched& S, const Epi& E) {
;     ...
;         for (int t = 0; t < nt; t += 2) {
;             const bool last = (t == nt - 2);
;             const char* a1 = cA + (size_t)(t + 1) * kstep;
;             const char* a2 = last ? nA : cA + (size_t)(t + 2) * kstep; const char* b2 = last ? nB : cB + (size_t)(t + 2) * kstep;
;     ...
;             PG8_LDB(B0, 1, 0); PG8_LDB(B1, 1, 1); PG8_SCHED; PG8_LDA(At, 1, 0); PG8_STAGE(PG8_SA(0, 1), a2 + hstep, voffA);
;             PG8_WAIT_V(8); PG8_WAIT_L(0); PG8_BAR; PG8_MMA(0, 0, At, B0); PG8_MMA(0, 1, At, B1); PG8_BAR; PG8_SCHED;
;             PG8_LDA(At, 1, 1); PG8_STAGE(PG8_SB(1, 0), b3, voffB); PG8_STAGE(PG8_SB(1, 1), b3 + hstep, voffB); PG8_STAGE(PG8_SA(1, 0), a3, voffA);
;             PG8_WAIT_V(8); PG8_WAIT_L(0); PG8_BAR; PG8_MMA(1, 0, At, B0); PG8_MMA(1, 1, At, B1); PG8_BAR; PG8_SCHED;
	s_add_i32 s71, 0, 0x18000
	s_add_i32 s72, 0, 0x1c000
	v_add_u32_e32 v140, s71, v190
	v_add_u32_e32 v172, s72, v190
	ds_read_b128 v[128:131], v140
	ds_read_b128 v[132:135], v140 offset:1024
	ds_read_b128 v[136:139], v140 offset:2048
	ds_read_b128 v[140:143], v140 offset:3072
	ds_read_b128 v[144:147], v172
	ds_read_b128 v[148:151], v172 offset:1024
	ds_read_b128 v[168:171], v172 offset:2048
	ds_read_b128 v[172:175], v172 offset:3072
	s_add_u32 s60, s60, 0x80000
	s_addc_u32 s61, s61, 0
	s_mov_b32 m0, s62
	ds_read_b128 v[178:181], v194 offset:32768
	ds_read_b128 v[182:185], v194 offset:33792
	ds_read_b128 v[196:199], v194 offset:34816
	ds_read_b128 v[200:203], v194 offset:35840
	ds_read_b128 v[204:207], v194 offset:36864
	ds_read_b128 v[208:211], v194 offset:37888
	ds_read_b128 v[212:215], v194 offset:38912
	ds_read_b128 v[216:219], v194 offset:39936
	global_load_lds_dwordx4 v152, s[60:61]
	s_mov_b32 m0, s63
	s_nop 0
	global_load_lds_dwordx4 v156, s[60:61]
	s_waitcnt vmcnt(8)
	s_waitcnt lgkmcnt(0)
	s_setprio 1
	s_barrier
	v_mfma_f32_16x16x32_bf16 v[124:127], v[128:131], v[178:181], v[124:127]
	v_mfma_f32_16x16x32_bf16 v[120:123], v[136:139], v[178:181], v[120:123]
	v_mfma_f32_16x16x32_bf16 v[108:111], v[128:131], v[196:199], v[108:111]
	v_mfma_f32_16x16x32_bf16 v[104:107], v[136:139], v[196:199], v[104:107]
	v_mfma_f32_16x16x32_bf16 v[92:95], v[128:131], v[204:207], v[92:95]
	v_mfma_f32_16x16x32_bf16 v[88:91], v[136:139], v[204:207], v[88:91]
	v_mfma_f32_16x16x32_bf16 v[76:79], v[128:131], v[212:215], v[76:79]
	v_mfma_f32_16x16x32_bf16 v[72:75], v[136:139], v[212:215], v[72:75]
	v_mfma_f32_16x16x32_bf16 v[124:127], v[132:135], v[182:185], v[124:127]
	v_mfma_f32_16x16x32_bf16 v[120:123], v[140:143], v[182:185], v[120:123]
	v_mfma_f32_16x16x32_bf16 v[108:111], v[132:135], v[200:203], v[108:111]
	v_mfma_f32_16x16x32_bf16 v[104:107], v[140:143], v[200:203], v[104:107]
	v_mfma_f32_16x16x32_bf16 v[92:95], v[132:135], v[208:211], v[92:95]
	v_mfma_f32_16x16x32_bf16 v[88:91], v[140:143], v[208:211], v[88:91]
	v_mfma_f32_16x16x32_bf16 v[76:79], v[132:135], v[216:219], v[76:79]
	v_mfma_f32_16x16x32_bf16 v[72:75], v[140:143], v[216:219], v[72:75]
	v_mfma_f32_16x16x32_bf16 v[116:119], v[144:147], v[178:181], v[116:119]
	v_mfma_f32_16x16x32_bf16 v[112:115], v[168:171], v[178:181], v[112:115]
	v_mfma_f32_16x16x32_bf16 v[100:103], v[144:147], v[196:199], v[100:103]
	v_mfma_f32_16x16x32_bf16 v[96:99], v[168:171], v[196:199], v[96:99]
	v_mfma_f32_16x16x32_bf16 v[84:87], v[144:147], v[204:207], v[84:87]
	v_mfma_f32_16x16x32_bf16 v[80:83], v[168:171], v[204:207], v[80:83]
	v_mfma_f32_16x16x32_bf16 v[68:71], v[144:147], v[212:215], v[68:71]
	v_mfma_f32_16x16x32_bf16 v[64:67], v[168:171], v[212:215], v[64:67]
	v_mfma_f32_16x16x32_bf16 v[116:119], v[148:151], v[182:185], v[116:119]
	v_mfma_f32_16x16x32_bf16 v[112:115], v[172:175], v[182:185], v[112:115]
	v_mfma_f32_16x16x32_bf16 v[100:103], v[148:151], v[200:203], v[100:103]
	v_mfma_f32_16x16x32_bf16 v[96:99], v[172:175], v[200:203], v[96:99]
	v_mfma_f32_16x16x32_bf16 v[84:87], v[148:151], v[208:211], v[84:87]
	v_mfma_f32_16x16x32_bf16 v[80:83], v[172:175], v[208:211], v[80:83]
	v_mfma_f32_16x16x32_bf16 v[68:71], v[148:151], v[216:219], v[68:71]
	v_mfma_f32_16x16x32_bf16 v[64:67], v[172:175], v[216:219], v[64:67]
	s_setprio 0
	s_barrier
	s_add_i32 s60, s71, s15
	s_mov_b32 m0, s60
	ds_read_b128 v[178:181], v194 offset:49152
	ds_read_b128 v[182:185], v194 offset:50176
	ds_read_b128 v[196:199], v194 offset:51200
	ds_read_b128 v[200:203], v194 offset:52224
	ds_read_b128 v[204:207], v194 offset:53248
	ds_read_b128 v[208:211], v194 offset:54272
	ds_read_b128 v[212:215], v194 offset:55296
	ds_read_b128 v[216:219], v194 offset:56320
	global_load_lds_dwordx4 v154, s[98:99]
	s_add_i32 m0, s60, 0x2000
	s_add_u32 s58, s58, 0x80080
	s_addc_u32 s59, s59, 0
	s_add_i32 s60, s72, s15
	global_load_lds_dwordx4 v158, s[98:99]
	s_mov_b32 m0, s60
	s_nop 0
	global_load_lds_dwordx4 v154, s[58:59]
	s_add_i32 m0, s60, 0x2000
	s_nop 0
	global_load_lds_dwordx4 v158, s[58:59]
	s_mov_b32 m0, s65
	s_nop 0
	global_load_lds_dwordx4 v152, s[100:101]
	s_mov_b32 m0, s66
	s_nop 0
	global_load_lds_dwordx4 v156, s[100:101]
	s_waitcnt vmcnt(8)
	s_waitcnt lgkmcnt(0)
	s_setprio 1
	s_barrier
	v_mfma_f32_16x16x32_bf16 v[60:63], v[128:131], v[178:181], v[60:63]
	v_mfma_f32_16x16x32_bf16 v[56:59], v[136:139], v[178:181], v[56:59]
	v_mfma_f32_16x16x32_bf16 v[44:47], v[128:131], v[196:199], v[44:47]
	v_mfma_f32_16x16x32_bf16 v[40:43], v[136:139], v[196:199], v[40:43]
	v_mfma_f32_16x16x32_bf16 v[28:31], v[128:131], v[204:207], v[28:31]
	v_mfma_f32_16x16x32_bf16 v[24:27], v[136:139], v[204:207], v[24:27]
	v_mfma_f32_16x16x32_bf16 v[12:15], v[128:131], v[212:215], v[12:15]
	v_mfma_f32_16x16x32_bf16 v[8:11], v[136:139], v[212:215], v[8:11]
	v_mfma_f32_16x16x32_bf16 v[60:63], v[132:135], v[182:185], v[60:63]
	v_mfma_f32_16x16x32_bf16 v[56:59], v[140:143], v[182:185], v[56:59]
	v_mfma_f32_16x16x32_bf16 v[44:47], v[132:135], v[200:203], v[44:47]
	v_mfma_f32_16x16x32_bf16 v[40:43], v[140:143], v[200:203], v[40:43]
	v_mfma_f32_16x16x32_bf16 v[28:31], v[132:135], v[208:211], v[28:31]
	v_mfma_f32_16x16x32_bf16 v[24:27], v[140:143], v[208:211], v[24:27]
	v_mfma_f32_16x16x32_bf16 v[12:15], v[132:135], v[216:219], v[12:15]
	v_mfma_f32_16x16x32_bf16 v[8:11], v[140:143], v[216:219], v[8:11]
	v_mfma_f32_16x16x32_bf16 v[52:55], v[144:147], v[178:181], v[52:55]
	v_mfma_f32_16x16x32_bf16 v[48:51], v[168:171], v[178:181], v[48:51]
	v_mfma_f32_16x16x32_bf16 v[36:39], v[144:147], v[196:199], v[36:39]
	v_mfma_f32_16x16x32_bf16 v[32:35], v[168:171], v[196:199], v[32:35]
	v_mfma_f32_16x16x32_bf16 v[20:23], v[144:147], v[204:207], v[20:23]
	v_mfma_f32_16x16x32_bf16 v[16:19], v[168:171], v[204:207], v[16:19]
	v_mfma_f32_16x16x32_bf16 v[4:7], v[144:147], v[212:215], v[4:7]
	v_mfma_f32_16x16x32_bf16 v[0:3], v[168:171], v[212:215], v[0:3]
	v_mfma_f32_16x16x32_bf16 v[52:55], v[148:151], v[182:185], v[52:55]
	v_mfma_f32_16x16x32_bf16 v[48:51], v[172:175], v[182:185], v[48:51]
	v_mfma_f32_16x16x32_bf16 v[36:39], v[148:151], v[200:203], v[36:39]
	v_mfma_f32_16x16x32_bf16 v[32:35], v[172:175], v[200:203], v[32:35]
	v_mfma_f32_16x16x32_bf16 v[20:23], v[148:151], v[208:211], v[20:23]
	v_mfma_f32_16x16x32_bf16 v[16:19], v[172:175], v[208:211], v[16:19]
	v_mfma_f32_16x16x32_bf16 v[4:7], v[148:151], v[216:219], v[4:7]
	v_mfma_f32_16x16x32_bf16 v[0:3], v[172:175], v[216:219], v[0:3]
	s_setprio 0
	s_barrier
	s_add_i32 s70, s70, 2
	s_add_u32 s50, s50, 0x100
	s_addc_u32 s51, s51, 0
	s_add_u32 s47, s47, 0x100
	s_addc_u32 s69, s69, 0
	s_cmp_gt_u32 s70, 29
	s_cbranch_scc0 .LBB0_626
	s_branch .Lsapad2
	s_nop 0
	s_nop 0
	s_nop 0
	s_nop 0
	s_nop 0
	s_nop 0
	s_nop 0
	s_nop 0
	s_nop 0
	s_nop 0
	s_nop 0
	s_nop 0
	s_nop 0
	s_nop 0
	s_nop 0
	s_nop 0
	s_nop 0
	s_nop 0
	s_nop 0
	s_nop 0
	s_nop 0
	s_nop 0
	s_nop 0
	s_nop 0
	s_nop 0
	s_nop 0
	s_nop 0
	s_nop 0
	s_nop 0
	s_nop 0
	s_nop 0
	s_nop 0
	s_nop 0
	s_nop 0
	s_nop 0
	s_nop 0

; #define PG8_STAGE(bufoff, gbase, voff) do { _Pragma("unroll") for (int _i = 0; _i < 2; ++_i) \
;         __builtin_amdgcn_global_load_lds((const unsigned*)((const char*)(gbase) + (voff)[_i]), (LAS unsigned*)(lds + (bufoff) + ldsw + _i * 8192), 16, 0, 0); } while (0)
; #define PG8_LDA(dst, b, h) do { _Pragma("unroll") for (int m = 0; m < 4; ++m) _Pragma("unroll") for (int k = 0; k < 2; ++k) dst[m][k] = *(const LAS bf16x8*)(lds + PG8_SA(b, h) + aoff + m * 2048 + k * 1024); } while (0)
; #define PG8_LDB(dst, b, h) do { _Pragma("unroll") for (int n = 0; n < 2; ++n) _Pragma("unroll") for (int k = 0; k < 2; ++k) dst[n][k] = *(const LAS bf16x8*)(lds + PG8_SB(b, h) + boff + n * 2048 + k * 1024); } while (0)
; #define PG8_MMA(ai, bj, At, Bt) do { __builtin_amdgcn_s_setprio(1); _Pragma("unroll") for (int m = 0; m < 4; ++m) _Pragma("unroll") for (int n = 0; n < 2; ++n) _Pragma("unroll") for (int k = 0; k < 2; ++k) \
;         acc[ai][bj][m][n] = __builtin_amdgcn_mfma_f32_16x16x32_bf16(Bt[n][k], At[m][k], acc[ai][bj][m][n], 0, 0, 0); __builtin_amdgcn_s_setprio(0); } while (0)
; #define PG8_WAIT_V(n) asm volatile("s_waitcnt vmcnt(" #n ")" ::: "memory")
; #define PG8_WAIT_L(n) asm volatile("s_waitcnt lgkmcnt(" #n ")" ::: "memory")
; #define PG8_BAR __builtin_amdgcn_s_barrier()
; #define PG8_SCHED __builtin_amdgcn_sched_barrier(0)
; template <class Epi, class Sched, bool ALIGN_EPI = false, bool SP2 = false>
; __device__ __forceinline__ void gemm_phase(LAS unsigned char* lds, const Gemm g, const Sched& S, const Epi& E) {
;     ...
;             if constexpr (SP2) {
;             PG8_LDB(B0, 0, 0); PG8_LDB(B1, 0, 1); PG8_SCHED; PG8_LDA(At, 0, 0); PG8_STAGE(PG8_SA(1, 1), a1 + hstep, voffA);
;             PG8_WAIT_V(8); PG8_WAIT_L(0); PG8_BAR; PG8_MMA(0, 0, At, B0); PG8_MMA(0, 1, At, B1); PG8_BAR; PG8_SCHED;
;             PG8_LDA(At, 0, 1); PG8_STAGE(PG8_SB(0, 0), b2, voffB); PG8_STAGE(PG8_SB(0, 1), b2 + hstep, voffB); PG8_STAGE(PG8_SA(0, 0), a2, voffA);
;             PG8_WAIT_V(8); PG8_WAIT_L(0); PG8_BAR; PG8_MMA(1, 0, At, B0); PG8_MMA(1, 1, At, B1); PG8_BAR; PG8_SCHED;
.LBB0_710:
	v_add_u32_e32 v169, s58, v150
	ds_read_b128 v[170:173], v169
	ds_read_b128 v[178:181], v169 offset:1024
	ds_read_b128 v[182:185], v169 offset:2048
	ds_read_b128 v[190:193], v169 offset:3072
	v_add_u32_e32 v169, s59, v150
	ds_read_b128 v[194:197], v169
	ds_read_b128 v[198:201], v169 offset:1024
	ds_read_b128 v[202:205], v169 offset:2048
	ds_read_b128 v[206:209], v169 offset:3072
	s_add_u32 s44, s40, 0xfff80080
	s_addc_u32 s45, s41, -1
	s_and_b64 s[42:43], s[42:43], exec
	s_cselect_b32 s45, s27, s45
	s_cselect_b32 s44, s62, s44
	s_cselect_b32 s43, s19, s16
	s_cselect_b32 s42, s63, s64
	s_add_i32 m0, s39, 0xc000
	ds_read_b128 v[210:213], v152
	ds_read_b128 v[214:217], v152 offset:1024
	ds_read_b128 v[218:221], v152 offset:2048
	ds_read_b128 v[222:225], v152 offset:3072
	ds_read_b128 v[226:229], v152 offset:4096
	ds_read_b128 v[230:233], v152 offset:5120
	ds_read_b128 v[234:237], v152 offset:6144
	ds_read_b128 v[238:241], v152 offset:7168
	global_load_lds_dwordx4 v138, s[40:41]
	s_add_i32 m0, s39, 0xe000
	s_nop 0
	global_load_lds_dwordx4 v140, s[40:41]
	s_waitcnt vmcnt(8)
	s_waitcnt lgkmcnt(0)
	s_setprio 1
	s_barrier
	v_mfma_f32_16x16x32_bf16 v[124:127], v[170:173], v[210:213], v[124:127]
	v_mfma_f32_16x16x32_bf16 v[120:123], v[182:185], v[210:213], v[120:123]
	v_mfma_f32_16x16x32_bf16 v[108:111], v[170:173], v[218:221], v[108:111]
	v_mfma_f32_16x16x32_bf16 v[104:107], v[182:185], v[218:221], v[104:107]
	v_mfma_f32_16x16x32_bf16 v[92:95], v[170:173], v[226:229], v[92:95]
	v_mfma_f32_16x16x32_bf16 v[88:91], v[182:185], v[226:229], v[88:91]
	v_mfma_f32_16x16x32_bf16 v[76:79], v[170:173], v[234:237], v[76:79]
	v_mfma_f32_16x16x32_bf16 v[72:75], v[182:185], v[234:237], v[72:75]
	v_mfma_f32_16x16x32_bf16 v[124:127], v[178:181], v[214:217], v[124:127]
	v_mfma_f32_16x16x32_bf16 v[120:123], v[190:193], v[214:217], v[120:123]
	v_mfma_f32_16x16x32_bf16 v[108:111], v[178:181], v[222:225], v[108:111]
	v_mfma_f32_16x16x32_bf16 v[104:107], v[190:193], v[222:225], v[104:107]
	v_mfma_f32_16x16x32_bf16 v[92:95], v[178:181], v[230:233], v[92:95]
	v_mfma_f32_16x16x32_bf16 v[88:91], v[190:193], v[230:233], v[88:91]
	v_mfma_f32_16x16x32_bf16 v[76:79], v[178:181], v[238:241], v[76:79]
	v_mfma_f32_16x16x32_bf16 v[72:75], v[190:193], v[238:241], v[72:75]
	v_mfma_f32_16x16x32_bf16 v[116:119], v[194:197], v[210:213], v[116:119]
	v_mfma_f32_16x16x32_bf16 v[112:115], v[202:205], v[210:213], v[112:115]
	v_mfma_f32_16x16x32_bf16 v[100:103], v[194:197], v[218:221], v[100:103]
	v_mfma_f32_16x16x32_bf16 v[96:99], v[202:205], v[218:221], v[96:99]
	v_mfma_f32_16x16x32_bf16 v[84:87], v[194:197], v[226:229], v[84:87]
	v_mfma_f32_16x16x32_bf16 v[80:83], v[202:205], v[226:229], v[80:83]
	v_mfma_f32_16x16x32_bf16 v[68:71], v[194:197], v[234:237], v[68:71]
	v_mfma_f32_16x16x32_bf16 v[64:67], v[202:205], v[234:237], v[64:67]
	v_mfma_f32_16x16x32_bf16 v[116:119], v[198:201], v[214:217], v[116:119]
	v_mfma_f32_16x16x32_bf16 v[112:115], v[206:209], v[214:217], v[112:115]
	v_mfma_f32_16x16x32_bf16 v[100:103], v[198:201], v[222:225], v[100:103]
	v_mfma_f32_16x16x32_bf16 v[96:99], v[206:209], v[222:225], v[96:99]
	v_mfma_f32_16x16x32_bf16 v[84:87], v[198:201], v[230:233], v[84:87]
	v_mfma_f32_16x16x32_bf16 v[80:83], v[206:209], v[230:233], v[80:83]
	v_mfma_f32_16x16x32_bf16 v[68:71], v[198:201], v[238:241], v[68:71]
	v_mfma_f32_16x16x32_bf16 v[64:67], v[206:209], v[238:241], v[64:67]
	s_setprio 0
	s_barrier
	s_add_u32 s100, s44, 0x80
	s_addc_u32 s101, s45, 0
	s_add_u32 s98, s42, 0x80
	s_addc_u32 s99, s43, 0
	s_add_i32 s65, s58, s15
	s_mov_b32 m0, s65
	ds_read_b128 v[210:213], v152 offset:16384
	ds_read_b128 v[214:217], v152 offset:17408
	ds_read_b128 v[218:221], v152 offset:18432
	ds_read_b128 v[222:225], v152 offset:19456
	ds_read_b128 v[226:229], v152 offset:20480
	ds_read_b128 v[230:233], v152 offset:21504
	ds_read_b128 v[234:237], v152 offset:22528
	ds_read_b128 v[238:241], v152 offset:23552
	global_load_lds_dwordx4 v132, s[42:43]
	s_add_i32 m0, s65, 0x2000
	s_add_u32 s66, s42, 0x80000
	s_addc_u32 s67, s43, 0
	s_add_i32 s65, s59, s15
	global_load_lds_dwordx4 v128, s[42:43]
	s_mov_b32 m0, s65
	s_nop 0
	global_load_lds_dwordx4 v132, s[66:67]
	s_add_i32 m0, s65, 0x2000
	s_nop 0
	global_load_lds_dwordx4 v128, s[66:67]
	s_mov_b32 m0, s39
	s_nop 0
	global_load_lds_dwordx4 v134, s[44:45]
	s_mov_b32 m0, s46
	s_nop 0
	global_load_lds_dwordx4 v130, s[44:45]
	s_waitcnt vmcnt(8)
	s_waitcnt lgkmcnt(0)
	s_setprio 1
	s_barrier
	v_mfma_f32_16x16x32_bf16 v[60:63], v[170:173], v[210:213], v[60:63]
	v_mfma_f32_16x16x32_bf16 v[56:59], v[182:185], v[210:213], v[56:59]
	v_mfma_f32_16x16x32_bf16 v[44:47], v[170:173], v[218:221], v[44:47]
	v_mfma_f32_16x16x32_bf16 v[40:43], v[182:185], v[218:221], v[40:43]
	v_mfma_f32_16x16x32_bf16 v[28:31], v[170:173], v[226:229], v[28:31]
	v_mfma_f32_16x16x32_bf16 v[24:27], v[182:185], v[226:229], v[24:27]
	v_mfma_f32_16x16x32_bf16 v[12:15], v[170:173], v[234:237], v[12:15]
	v_mfma_f32_16x16x32_bf16 v[8:11], v[182:185], v[234:237], v[8:11]
	v_mfma_f32_16x16x32_bf16 v[60:63], v[178:181], v[214:217], v[60:63]
	v_mfma_f32_16x16x32_bf16 v[56:59], v[190:193], v[214:217], v[56:59]
	v_mfma_f32_16x16x32_bf16 v[44:47], v[178:181], v[222:225], v[44:47]
	v_mfma_f32_16x16x32_bf16 v[40:43], v[190:193], v[222:225], v[40:43]
	v_mfma_f32_16x16x32_bf16 v[28:31], v[178:181], v[230:233], v[28:31]
	v_mfma_f32_16x16x32_bf16 v[24:27], v[190:193], v[230:233], v[24:27]
	v_mfma_f32_16x16x32_bf16 v[12:15], v[178:181], v[238:241], v[12:15]
	v_mfma_f32_16x16x32_bf16 v[8:11], v[190:193], v[238:241], v[8:11]
	v_mfma_f32_16x16x32_bf16 v[52:55], v[194:197], v[210:213], v[52:55]
	v_mfma_f32_16x16x32_bf16 v[48:51], v[202:205], v[210:213], v[48:51]
	v_mfma_f32_16x16x32_bf16 v[36:39], v[194:197], v[218:221], v[36:39]
	v_mfma_f32_16x16x32_bf16 v[32:35], v[202:205], v[218:221], v[32:35]
	v_mfma_f32_16x16x32_bf16 v[20:23], v[194:197], v[226:229], v[20:23]
	v_mfma_f32_16x16x32_bf16 v[16:19], v[202:205], v[226:229], v[16:19]
	v_mfma_f32_16x16x32_bf16 v[4:7], v[194:197], v[234:237], v[4:7]
	v_mfma_f32_16x16x32_bf16 v[0:3], v[202:205], v[234:237], v[0:3]
	v_mfma_f32_16x16x32_bf16 v[52:55], v[198:201], v[214:217], v[52:55]
	v_mfma_f32_16x16x32_bf16 v[48:51], v[206:209], v[214:217], v[48:51]
	v_mfma_f32_16x16x32_bf16 v[36:39], v[198:201], v[222:225], v[36:39]
	v_mfma_f32_16x16x32_bf16 v[32:35], v[206:209], v[222:225], v[32:35]
	v_mfma_f32_16x16x32_bf16 v[20:23], v[198:201], v[230:233], v[20:23]
	v_mfma_f32_16x16x32_bf16 v[16:19], v[206:209], v[230:233], v[16:19]
	v_mfma_f32_16x16x32_bf16 v[4:7], v[198:201], v[238:241], v[4:7]
	v_mfma_f32_16x16x32_bf16 v[0:3], v[206:209], v[238:241], v[0:3]
	s_setprio 0
	s_barrier
; #define PG8_STAGE(bufoff, gbase, voff) do { _Pragma("unroll") for (int _i = 0; _i < 2; ++_i) \
;         __builtin_amdgcn_global_load_lds((const unsigned*)((const char*)(gbase) + (voff)[_i]), (LAS unsigned*)(lds + (bufoff) + ldsw + _i * 8192), 16, 0, 0); } while (0)
; #define PG8_LDA(dst, b, h) do { _Pragma("unroll") for (int m = 0; m < 4; ++m) _Pragma("unroll") for (int k = 0; k < 2; ++k) dst[m][k] = *(const LAS bf16x8*)(lds + PG8_SA(b, h) + aoff + m * 2048 + k * 1024); } while (0)
; #define PG8_LDB(dst, b, h) do { _Pragma("unroll") for (int n = 0; n < 2; ++n) _Pragma("unroll") for (int k = 0; k < 2; ++k) dst[n][k] = *(const LAS bf16x8*)(lds + PG8_SB(b, h) + boff + n * 2048 + k * 1024); } while (0)
; #define PG8_MMA(ai, bj, At, Bt) do { __builtin_amdgcn_s_setprio(1); _Pragma("unroll") for (int m = 0; m < 4; ++m) _Pragma("unroll") for (int n = 0; n < 2; ++n) _Pragma("unroll") for (int k = 0; k < 2; ++k) \
;         acc[ai][bj][m][n] = __builtin_amdgcn_mfma_f32_16x16x32_bf16(Bt[n][k], At[m][k], acc[ai][bj][m][n], 0, 0, 0); __builtin_amdgcn_s_setprio(0); } while (0)
; #define PG8_WAIT_V(n) asm volatile("s_waitcnt vmcnt(" #n ")" ::: "memory")
; #define PG8_WAIT_L(n) asm volatile("s_waitcnt lgkmcnt(" #n ")" ::: "memory")
; #define PG8_BAR __builtin_amdgcn_s_barrier()
; #define PG8_SCHED __builtin_amdgcn_sched_barrier(0)
; template <class Epi, class Sched, bool ALIGN_EPI = false, bool SP2 = false>
; __device__ __forceinline__ void gemm_phase(LAS unsigned char* lds, const Gemm g, const Sched& S, const Epi& E) {
;     ...
;             PG8_LDB(B0, 1, 0); PG8_LDB(B1, 1, 1); PG8_SCHED; PG8_LDA(At, 1, 0); PG8_STAGE(PG8_SA(0, 1), a2 + hstep, voffA);
;             PG8_WAIT_V(8); PG8_WAIT_L(0); PG8_BAR; PG8_MMA(0, 0, At, B0); PG8_MMA(0, 1, At, B1); PG8_BAR; PG8_SCHED;
;             PG8_LDA(At, 1, 1); PG8_STAGE(PG8_SB(1, 0), b3, voffB); PG8_STAGE(PG8_SB(1, 1), b3 + hstep, voffB); PG8_STAGE(PG8_SA(1, 0), a3, voffA);
;             PG8_WAIT_V(8); PG8_WAIT_L(0); PG8_BAR; PG8_MMA(1, 0, At, B0); PG8_MMA(1, 1, At, B1); PG8_BAR; PG8_SCHED;
	s_add_i32 s65, 0, 0x18000
	v_add_u32_e32 v169, s65, v150
	s_add_i32 s66, 0, 0x1c000
	ds_read_b128 v[170:173], v169
	ds_read_b128 v[178:181], v169 offset:1024
	ds_read_b128 v[182:185], v169 offset:2048
	ds_read_b128 v[190:193], v169 offset:3072
	v_add_u32_e32 v169, s66, v150
	ds_read_b128 v[194:197], v169
	ds_read_b128 v[198:201], v169 offset:1024
	ds_read_b128 v[202:205], v169 offset:2048
	ds_read_b128 v[206:209], v169 offset:3072
	s_add_u32 s44, s44, 0x80000
	s_addc_u32 s45, s45, 0
	s_mov_b32 m0, s47
	ds_read_b128 v[210:213], v152 offset:32768
	ds_read_b128 v[214:217], v152 offset:33792
	ds_read_b128 v[218:221], v152 offset:34816
	ds_read_b128 v[222:225], v152 offset:35840
	ds_read_b128 v[226:229], v152 offset:36864
	ds_read_b128 v[230:233], v152 offset:37888
	ds_read_b128 v[234:237], v152 offset:38912
	ds_read_b128 v[238:241], v152 offset:39936
	global_load_lds_dwordx4 v134, s[44:45]
	s_mov_b32 m0, s48
	s_nop 0
	global_load_lds_dwordx4 v130, s[44:45]
	s_waitcnt vmcnt(8)
	s_waitcnt lgkmcnt(0)
	s_setprio 1
	s_barrier
	v_mfma_f32_16x16x32_bf16 v[124:127], v[170:173], v[210:213], v[124:127]
	v_mfma_f32_16x16x32_bf16 v[120:123], v[182:185], v[210:213], v[120:123]
	v_mfma_f32_16x16x32_bf16 v[108:111], v[170:173], v[218:221], v[108:111]
	v_mfma_f32_16x16x32_bf16 v[104:107], v[182:185], v[218:221], v[104:107]
	v_mfma_f32_16x16x32_bf16 v[92:95], v[170:173], v[226:229], v[92:95]
	v_mfma_f32_16x16x32_bf16 v[88:91], v[182:185], v[226:229], v[88:91]
	v_mfma_f32_16x16x32_bf16 v[76:79], v[170:173], v[234:237], v[76:79]
	v_mfma_f32_16x16x32_bf16 v[72:75], v[182:185], v[234:237], v[72:75]
	v_mfma_f32_16x16x32_bf16 v[124:127], v[178:181], v[214:217], v[124:127]
	v_mfma_f32_16x16x32_bf16 v[120:123], v[190:193], v[214:217], v[120:123]
	v_mfma_f32_16x16x32_bf16 v[108:111], v[178:181], v[222:225], v[108:111]
	v_mfma_f32_16x16x32_bf16 v[104:107], v[190:193], v[222:225], v[104:107]
	v_mfma_f32_16x16x32_bf16 v[92:95], v[178:181], v[230:233], v[92:95]
	v_mfma_f32_16x16x32_bf16 v[88:91], v[190:193], v[230:233], v[88:91]
	v_mfma_f32_16x16x32_bf16 v[76:79], v[178:181], v[238:241], v[76:79]
	v_mfma_f32_16x16x32_bf16 v[72:75], v[190:193], v[238:241], v[72:75]
	v_mfma_f32_16x16x32_bf16 v[116:119], v[194:197], v[210:213], v[116:119]
	v_mfma_f32_16x16x32_bf16 v[112:115], v[202:205], v[210:213], v[112:115]
	v_mfma_f32_16x16x32_bf16 v[100:103], v[194:197], v[218:221], v[100:103]
	v_mfma_f32_16x16x32_bf16 v[96:99], v[202:205], v[218:221], v[96:99]
	v_mfma_f32_16x16x32_bf16 v[84:87], v[194:197], v[226:229], v[84:87]
	v_mfma_f32_16x16x32_bf16 v[80:83], v[202:205], v[226:229], v[80:83]
	v_mfma_f32_16x16x32_bf16 v[68:71], v[194:197], v[234:237], v[68:71]
	v_mfma_f32_16x16x32_bf16 v[64:67], v[202:205], v[234:237], v[64:67]
	v_mfma_f32_16x16x32_bf16 v[116:119], v[198:201], v[214:217], v[116:119]
	v_mfma_f32_16x16x32_bf16 v[112:115], v[206:209], v[214:217], v[112:115]
	v_mfma_f32_16x16x32_bf16 v[100:103], v[198:201], v[222:225], v[100:103]
	v_mfma_f32_16x16x32_bf16 v[96:99], v[206:209], v[222:225], v[96:99]
	v_mfma_f32_16x16x32_bf16 v[84:87], v[198:201], v[230:233], v[84:87]
	v_mfma_f32_16x16x32_bf16 v[80:83], v[206:209], v[230:233], v[80:83]
	v_mfma_f32_16x16x32_bf16 v[68:71], v[198:201], v[238:241], v[68:71]
	v_mfma_f32_16x16x32_bf16 v[64:67], v[206:209], v[238:241], v[64:67]
	s_setprio 0
	s_barrier
	s_add_i32 s44, s65, s15
	s_mov_b32 m0, s44
	ds_read_b128 v[210:213], v152 offset:49152
	ds_read_b128 v[214:217], v152 offset:50176
	ds_read_b128 v[218:221], v152 offset:51200
	ds_read_b128 v[222:225], v152 offset:52224
	ds_read_b128 v[226:229], v152 offset:53248
	ds_read_b128 v[230:233], v152 offset:54272
	ds_read_b128 v[234:237], v152 offset:55296
	ds_read_b128 v[238:241], v152 offset:56320
	global_load_lds_dwordx4 v132, s[98:99]
	s_add_i32 m0, s44, 0x2000
	s_add_u32 s42, s42, 0x80080
	s_addc_u32 s43, s43, 0
	s_add_i32 s44, s66, s15
	global_load_lds_dwordx4 v128, s[98:99]
	s_mov_b32 m0, s44
	s_nop 0
	global_load_lds_dwordx4 v132, s[42:43]
	s_add_i32 m0, s44, 0x2000
	s_nop 0
	global_load_lds_dwordx4 v128, s[42:43]
	s_mov_b32 m0, s50
	s_nop 0
	global_load_lds_dwordx4 v134, s[100:101]
	s_mov_b32 m0, s51
	s_nop 0
	global_load_lds_dwordx4 v130, s[100:101]
	s_waitcnt vmcnt(8)
	s_waitcnt lgkmcnt(0)
	s_setprio 1
	s_barrier
	v_mfma_f32_16x16x32_bf16 v[60:63], v[170:173], v[210:213], v[60:63]
	v_mfma_f32_16x16x32_bf16 v[56:59], v[182:185], v[210:213], v[56:59]
	v_mfma_f32_16x16x32_bf16 v[44:47], v[170:173], v[218:221], v[44:47]
	v_mfma_f32_16x16x32_bf16 v[40:43], v[182:185], v[218:221], v[40:43]
	v_mfma_f32_16x16x32_bf16 v[28:31], v[170:173], v[226:229], v[28:31]
	v_mfma_f32_16x16x32_bf16 v[24:27], v[182:185], v[226:229], v[24:27]
	v_mfma_f32_16x16x32_bf16 v[12:15], v[170:173], v[234:237], v[12:15]
	v_mfma_f32_16x16x32_bf16 v[8:11], v[182:185], v[234:237], v[8:11]
	v_mfma_f32_16x16x32_bf16 v[60:63], v[178:181], v[214:217], v[60:63]
	v_mfma_f32_16x16x32_bf16 v[56:59], v[190:193], v[214:217], v[56:59]
	v_mfma_f32_16x16x32_bf16 v[44:47], v[178:181], v[222:225], v[44:47]
	v_mfma_f32_16x16x32_bf16 v[40:43], v[190:193], v[222:225], v[40:43]
	v_mfma_f32_16x16x32_bf16 v[28:31], v[178:181], v[230:233], v[28:31]
	v_mfma_f32_16x16x32_bf16 v[24:27], v[190:193], v[230:233], v[24:27]
	v_mfma_f32_16x16x32_bf16 v[12:15], v[178:181], v[238:241], v[12:15]
	v_mfma_f32_16x16x32_bf16 v[8:11], v[190:193], v[238:241], v[8:11]
	v_mfma_f32_16x16x32_bf16 v[52:55], v[194:197], v[210:213], v[52:55]
	v_mfma_f32_16x16x32_bf16 v[48:51], v[202:205], v[210:213], v[48:51]
	v_mfma_f32_16x16x32_bf16 v[36:39], v[194:197], v[218:221], v[36:39]
	v_mfma_f32_16x16x32_bf16 v[32:35], v[202:205], v[218:221], v[32:35]
	v_mfma_f32_16x16x32_bf16 v[20:23], v[194:197], v[226:229], v[20:23]
	v_mfma_f32_16x16x32_bf16 v[16:19], v[202:205], v[226:229], v[16:19]
	v_mfma_f32_16x16x32_bf16 v[4:7], v[194:197], v[234:237], v[4:7]
	v_mfma_f32_16x16x32_bf16 v[0:3], v[202:205], v[234:237], v[0:3]
	v_mfma_f32_16x16x32_bf16 v[52:55], v[198:201], v[214:217], v[52:55]
	v_mfma_f32_16x16x32_bf16 v[48:51], v[206:209], v[214:217], v[48:51]
	v_mfma_f32_16x16x32_bf16 v[36:39], v[198:201], v[222:225], v[36:39]
	v_mfma_f32_16x16x32_bf16 v[32:35], v[206:209], v[222:225], v[32:35]
	v_mfma_f32_16x16x32_bf16 v[20:23], v[198:201], v[230:233], v[20:23]
	v_mfma_f32_16x16x32_bf16 v[16:19], v[206:209], v[230:233], v[16:19]
	v_mfma_f32_16x16x32_bf16 v[4:7], v[198:201], v[238:241], v[4:7]
	v_mfma_f32_16x16x32_bf16 v[0:3], v[206:209], v[238:241], v[0:3]
	s_setprio 0
	s_barrier
	s_add_i32 s17, s17, 2
	s_add_u32 s40, s40, 0x100
	s_addc_u32 s41, s41, 0
	s_add_u32 s64, s64, 0x100
	s_addc_u32 s16, s16, 0
	s_cmp_gt_u32 s17, 29
	s_cbranch_scc1 .LBB0_713
;     __device__ __forceinline__ Pre pre(const Unit& u, int wr, int fr) const { return load_rows8(ss, u, wr, fr); }
;     __device__ __forceinline__ Pre pre(const Unit& u, int wr, int fr) const { return load_rows8(ss, u, wr, fr); }
; template <class Epi, class Sched, bool ALIGN_EPI = false, bool SP2 = false>
; __device__ __forceinline__ void gemm_phase(LAS unsigned char* lds, const Gemm g, const Sched& S, const Epi& E) {
;     ...
;             const bool last = (t == nt - 2);
;             const char* a1 = cA + (size_t)(t + 1) * kstep;
;             const char* a2 = last ? nA : cA + (size_t)(t + 2) * kstep; const char* b2 = last ? nB : cB + (size_t)(t + 2) * kstep;
;             const char* a3 = a2 + kstep; const char* b3 = b2 + kstep;
;             if (last && has_next) { S.a_ready(nxt); pre_nxt = E.pre(nxt, wr, fr); }
; __device__ __forceinline__ PreRows load_rows8(const float* ss, const Unit& u, int wr, int fr) {
;     PreRows p; const float* b = ss + u.pm * BM + wr * 64 + fr;
; #pragma unroll
;     for (int ai = 0; ai < 2; ++ai)
; #pragma unroll
;         for (int m = 0; m < 4; ++m) p.v[ai * 4 + m] = b[ai * HALF + m * 16];
;     return p;
.LBB0_711:
	s_cmp_eq_u32 s17, 28
	s_cselect_b64 s[42:43], -1, 0
	s_and_b64 s[44:45], s[6:7], s[42:43]
	s_andn2_b64 vcc, exec, s[44:45]
	s_cbranch_vccnz .LBB0_710
	global_load_dword v155, v[146:147], off
	global_load_dword v156, v[146:147], off offset:64
	global_load_dword v157, v[146:147], off offset:128
	global_load_dword v158, v[146:147], off offset:192
	global_load_dword v159, v[146:147], off offset:512
	global_load_dword v161, v[146:147], off offset:576
	global_load_dword v162, v[146:147], off offset:640
	global_load_dword v163, v[146:147], off offset:704
	s_branch .LBB0_710
	s_nop 0
	s_nop 0
	s_nop 0
	s_nop 0
	s_nop 0
	s_nop 0
	s_nop 0
	s_nop 0
	s_nop 0
	s_nop 0
	s_nop 0
	s_nop 0
	s_nop 0
	s_nop 0
	s_nop 0
	s_nop 0
	s_nop 0
	s_nop 0
	s_nop 0
	s_nop 0
	s_nop 0
	s_nop 0
	s_nop 0
	s_nop 0
	s_nop 0
	s_nop 0
	s_nop 0
	s_nop 0
	s_nop 0
	s_nop 0
	s_nop 0
	s_nop 0
	s_nop 0
	s_nop 0
	s_nop 0
	s_nop 0
	s_nop 0

; #define PG8_STAGE(bufoff, gbase, voff) do { _Pragma("unroll") for (int _i = 0; _i < 2; ++_i) \
;         __builtin_amdgcn_global_load_lds((const unsigned*)((const char*)(gbase) + (voff)[_i]), (LAS unsigned*)(lds + (bufoff) + ldsw + _i * 8192), 16, 0, 0); } while (0)
; #define PG8_LDA(dst, b, h) do { _Pragma("unroll") for (int m = 0; m < 4; ++m) _Pragma("unroll") for (int k = 0; k < 2; ++k) dst[m][k] = *(const LAS bf16x8*)(lds + PG8_SA(b, h) + aoff + m * 2048 + k * 1024); } while (0)
; #define PG8_LDB(dst, b, h) do { _Pragma("unroll") for (int n = 0; n < 2; ++n) _Pragma("unroll") for (int k = 0; k < 2; ++k) dst[n][k] = *(const LAS bf16x8*)(lds + PG8_SB(b, h) + boff + n * 2048 + k * 1024); } while (0)
; #define PG8_MMA(ai, bj, At, Bt) do { __builtin_amdgcn_s_setprio(1); _Pragma("unroll") for (int m = 0; m < 4; ++m) _Pragma("unroll") for (int n = 0; n < 2; ++n) _Pragma("unroll") for (int k = 0; k < 2; ++k) \
;         acc[ai][bj][m][n] = __builtin_amdgcn_mfma_f32_16x16x32_bf16(Bt[n][k], At[m][k], acc[ai][bj][m][n], 0, 0, 0); __builtin_amdgcn_s_setprio(0); } while (0)
; #define PG8_WAIT_V(n) asm volatile("s_waitcnt vmcnt(" #n ")" ::: "memory")
; #define PG8_WAIT_L(n) asm volatile("s_waitcnt lgkmcnt(" #n ")" ::: "memory")
; #define PG8_BAR __builtin_amdgcn_s_barrier()
; #define PG8_SCHED __builtin_amdgcn_sched_barrier(0)
; template <class Epi, class Sched, bool ALIGN_EPI = false, bool SP2 = false>
; __device__ __forceinline__ void gemm_phase(LAS unsigned char* lds, const Gemm g, const Sched& S, const Epi& E) {
;     ...
;             if constexpr (SP2) {
;             PG8_LDB(B0, 0, 0); PG8_LDB(B1, 0, 1); PG8_SCHED; PG8_LDA(At, 0, 0); PG8_STAGE(PG8_SA(1, 1), a1 + hstep, voffA);
;             PG8_WAIT_V(8); PG8_WAIT_L(0); PG8_BAR; PG8_MMA(0, 0, At, B0); PG8_MMA(0, 1, At, B1); PG8_BAR; PG8_SCHED;
;             PG8_LDA(At, 0, 1); PG8_STAGE(PG8_SB(0, 0), b2, voffB); PG8_STAGE(PG8_SB(0, 1), b2 + hstep, voffB); PG8_STAGE(PG8_SA(0, 0), a2, voffA);
;             PG8_WAIT_V(8); PG8_WAIT_L(0); PG8_BAR; PG8_MMA(1, 0, At, B0); PG8_MMA(1, 1, At, B1); PG8_BAR; PG8_SCHED;
.LBB0_794:
	ds_read_b128 v[128:131], v191
	ds_read_b128 v[132:135], v191 offset:1024
	ds_read_b128 v[136:139], v191 offset:2048
	ds_read_b128 v[140:143], v191 offset:3072
	ds_read_b128 v[144:147], v192
	ds_read_b128 v[148:151], v192 offset:1024
	ds_read_b128 v[168:171], v192 offset:2048
	ds_read_b128 v[172:175], v192 offset:3072
	s_add_u32 s38, s36, 0x100
	s_addc_u32 s39, s37, 0
	s_cmpk_eq_i32 s62, 0x54
	s_cselect_b32 s43, s1, s39
	s_cselect_b32 s42, s0, s38
	s_cselect_b32 s41, s29, s17
	s_cselect_b32 s40, s28, s16
	s_add_i32 m0, s35, 0xc000
	ds_read_b128 v[178:181], v193
	ds_read_b128 v[182:185], v193 offset:1024
	ds_read_b128 v[194:197], v193 offset:2048
	ds_read_b128 v[198:201], v193 offset:3072
	ds_read_b128 v[202:205], v193 offset:4096
	ds_read_b128 v[206:209], v193 offset:5120
	ds_read_b128 v[210:213], v193 offset:6144
	ds_read_b128 v[214:217], v193 offset:7168
	global_load_lds_dwordx4 v160, s[36:37]
	s_add_i32 m0, s35, 0xe000
	s_nop 0
	global_load_lds_dwordx4 v162, s[36:37]
	s_waitcnt vmcnt(8)
	s_waitcnt lgkmcnt(0)
	s_setprio 1
	s_barrier
	v_mfma_f32_16x16x32_bf16 v[124:127], v[128:131], v[178:181], v[124:127]
	v_mfma_f32_16x16x32_bf16 v[120:123], v[136:139], v[178:181], v[120:123]
	v_mfma_f32_16x16x32_bf16 v[108:111], v[128:131], v[194:197], v[108:111]
	v_mfma_f32_16x16x32_bf16 v[104:107], v[136:139], v[194:197], v[104:107]
	v_mfma_f32_16x16x32_bf16 v[92:95], v[128:131], v[202:205], v[92:95]
	v_mfma_f32_16x16x32_bf16 v[88:91], v[136:139], v[202:205], v[88:91]
	v_mfma_f32_16x16x32_bf16 v[76:79], v[128:131], v[210:213], v[76:79]
	v_mfma_f32_16x16x32_bf16 v[72:75], v[136:139], v[210:213], v[72:75]
	v_mfma_f32_16x16x32_bf16 v[124:127], v[132:135], v[182:185], v[124:127]
	v_mfma_f32_16x16x32_bf16 v[120:123], v[140:143], v[182:185], v[120:123]
	v_mfma_f32_16x16x32_bf16 v[108:111], v[132:135], v[198:201], v[108:111]
	v_mfma_f32_16x16x32_bf16 v[104:107], v[140:143], v[198:201], v[104:107]
	v_mfma_f32_16x16x32_bf16 v[92:95], v[132:135], v[206:209], v[92:95]
	v_mfma_f32_16x16x32_bf16 v[88:91], v[140:143], v[206:209], v[88:91]
	v_mfma_f32_16x16x32_bf16 v[76:79], v[132:135], v[214:217], v[76:79]
	v_mfma_f32_16x16x32_bf16 v[72:75], v[140:143], v[214:217], v[72:75]
	v_mfma_f32_16x16x32_bf16 v[116:119], v[144:147], v[178:181], v[116:119]
	v_mfma_f32_16x16x32_bf16 v[112:115], v[168:171], v[178:181], v[112:115]
	v_mfma_f32_16x16x32_bf16 v[100:103], v[144:147], v[194:197], v[100:103]
	v_mfma_f32_16x16x32_bf16 v[96:99], v[168:171], v[194:197], v[96:99]
	v_mfma_f32_16x16x32_bf16 v[84:87], v[144:147], v[202:205], v[84:87]
	v_mfma_f32_16x16x32_bf16 v[80:83], v[168:171], v[202:205], v[80:83]
	v_mfma_f32_16x16x32_bf16 v[68:71], v[144:147], v[210:213], v[68:71]
	v_mfma_f32_16x16x32_bf16 v[64:67], v[168:171], v[210:213], v[64:67]
	v_mfma_f32_16x16x32_bf16 v[116:119], v[148:151], v[182:185], v[116:119]
	v_mfma_f32_16x16x32_bf16 v[112:115], v[172:175], v[182:185], v[112:115]
	v_mfma_f32_16x16x32_bf16 v[100:103], v[148:151], v[198:201], v[100:103]
	v_mfma_f32_16x16x32_bf16 v[96:99], v[172:175], v[198:201], v[96:99]
	v_mfma_f32_16x16x32_bf16 v[84:87], v[148:151], v[206:209], v[84:87]
	v_mfma_f32_16x16x32_bf16 v[80:83], v[172:175], v[206:209], v[80:83]
	v_mfma_f32_16x16x32_bf16 v[68:71], v[148:151], v[214:217], v[68:71]
	v_mfma_f32_16x16x32_bf16 v[64:67], v[172:175], v[214:217], v[64:67]
	s_setprio 0
	s_barrier
	s_add_u32 s100, s42, 0x80
	s_addc_u32 s101, s43, 0
	s_add_u32 s98, s40, 0x80
	s_addc_u32 s99, s41, 0
	s_add_i32 s36, s50, s15
	s_mov_b32 m0, s36
	ds_read_b128 v[178:181], v193 offset:16384
	ds_read_b128 v[182:185], v193 offset:17408
	ds_read_b128 v[194:197], v193 offset:18432
	ds_read_b128 v[198:201], v193 offset:19456
	ds_read_b128 v[202:205], v193 offset:20480
	ds_read_b128 v[206:209], v193 offset:21504
	ds_read_b128 v[210:213], v193 offset:22528
	ds_read_b128 v[214:217], v193 offset:23552
	global_load_lds_dwordx4 v154, s[40:41]
	s_add_i32 m0, s36, 0x2000
	s_add_u32 s36, s40, 0x160000
	s_addc_u32 s37, s41, 0
	s_add_i32 s63, s51, s15
	global_load_lds_dwordx4 v158, s[40:41]
	s_mov_b32 m0, s63
	s_nop 0
	global_load_lds_dwordx4 v154, s[36:37]
	s_add_i32 m0, s63, 0x2000
	s_nop 0
	global_load_lds_dwordx4 v158, s[36:37]
	s_mov_b32 m0, s35
	s_nop 0
	global_load_lds_dwordx4 v152, s[42:43]
	s_mov_b32 m0, s44
	s_nop 0
	global_load_lds_dwordx4 v156, s[42:43]
	s_waitcnt vmcnt(8)
	s_waitcnt lgkmcnt(0)
	s_setprio 1
	s_barrier
	v_mfma_f32_16x16x32_bf16 v[60:63], v[128:131], v[178:181], v[60:63]
	v_mfma_f32_16x16x32_bf16 v[56:59], v[136:139], v[178:181], v[56:59]
	v_mfma_f32_16x16x32_bf16 v[44:47], v[128:131], v[194:197], v[44:47]
	v_mfma_f32_16x16x32_bf16 v[40:43], v[136:139], v[194:197], v[40:43]
	v_mfma_f32_16x16x32_bf16 v[28:31], v[128:131], v[202:205], v[28:31]
	v_mfma_f32_16x16x32_bf16 v[24:27], v[136:139], v[202:205], v[24:27]
	v_mfma_f32_16x16x32_bf16 v[12:15], v[128:131], v[210:213], v[12:15]
	v_mfma_f32_16x16x32_bf16 v[8:11], v[136:139], v[210:213], v[8:11]
	v_mfma_f32_16x16x32_bf16 v[60:63], v[132:135], v[182:185], v[60:63]
	v_mfma_f32_16x16x32_bf16 v[56:59], v[140:143], v[182:185], v[56:59]
	v_mfma_f32_16x16x32_bf16 v[44:47], v[132:135], v[198:201], v[44:47]
	v_mfma_f32_16x16x32_bf16 v[40:43], v[140:143], v[198:201], v[40:43]
	v_mfma_f32_16x16x32_bf16 v[28:31], v[132:135], v[206:209], v[28:31]
	v_mfma_f32_16x16x32_bf16 v[24:27], v[140:143], v[206:209], v[24:27]
	v_mfma_f32_16x16x32_bf16 v[12:15], v[132:135], v[214:217], v[12:15]
	v_mfma_f32_16x16x32_bf16 v[8:11], v[140:143], v[214:217], v[8:11]
	v_mfma_f32_16x16x32_bf16 v[52:55], v[144:147], v[178:181], v[52:55]
	v_mfma_f32_16x16x32_bf16 v[48:51], v[168:171], v[178:181], v[48:51]
	v_mfma_f32_16x16x32_bf16 v[36:39], v[144:147], v[194:197], v[36:39]
	v_mfma_f32_16x16x32_bf16 v[32:35], v[168:171], v[194:197], v[32:35]
	v_mfma_f32_16x16x32_bf16 v[20:23], v[144:147], v[202:205], v[20:23]
	v_mfma_f32_16x16x32_bf16 v[16:19], v[168:171], v[202:205], v[16:19]
	v_mfma_f32_16x16x32_bf16 v[4:7], v[144:147], v[210:213], v[4:7]
	v_mfma_f32_16x16x32_bf16 v[0:3], v[168:171], v[210:213], v[0:3]
	v_mfma_f32_16x16x32_bf16 v[52:55], v[148:151], v[182:185], v[52:55]
	v_mfma_f32_16x16x32_bf16 v[48:51], v[172:175], v[182:185], v[48:51]
	v_mfma_f32_16x16x32_bf16 v[36:39], v[148:151], v[198:201], v[36:39]
	v_mfma_f32_16x16x32_bf16 v[32:35], v[172:175], v[198:201], v[32:35]
	v_mfma_f32_16x16x32_bf16 v[20:23], v[148:151], v[206:209], v[20:23]
	v_mfma_f32_16x16x32_bf16 v[16:19], v[172:175], v[206:209], v[16:19]
	v_mfma_f32_16x16x32_bf16 v[4:7], v[148:151], v[214:217], v[4:7]
	v_mfma_f32_16x16x32_bf16 v[0:3], v[172:175], v[214:217], v[0:3]
	s_setprio 0
	s_barrier
; #define PG8_STAGE(bufoff, gbase, voff) do { _Pragma("unroll") for (int _i = 0; _i < 2; ++_i) \
;         __builtin_amdgcn_global_load_lds((const unsigned*)((const char*)(gbase) + (voff)[_i]), (LAS unsigned*)(lds + (bufoff) + ldsw + _i * 8192), 16, 0, 0); } while (0)
; #define PG8_LDA(dst, b, h) do { _Pragma("unroll") for (int m = 0; m < 4; ++m) _Pragma("unroll") for (int k = 0; k < 2; ++k) dst[m][k] = *(const LAS bf16x8*)(lds + PG8_SA(b, h) + aoff + m * 2048 + k * 1024); } while (0)
; #define PG8_LDB(dst, b, h) do { _Pragma("unroll") for (int n = 0; n < 2; ++n) _Pragma("unroll") for (int k = 0; k < 2; ++k) dst[n][k] = *(const LAS bf16x8*)(lds + PG8_SB(b, h) + boff + n * 2048 + k * 1024); } while (0)
; #define PG8_MMA(ai, bj, At, Bt) do { __builtin_amdgcn_s_setprio(1); _Pragma("unroll") for (int m = 0; m < 4; ++m) _Pragma("unroll") for (int n = 0; n < 2; ++n) _Pragma("unroll") for (int k = 0; k < 2; ++k) \
;         acc[ai][bj][m][n] = __builtin_amdgcn_mfma_f32_16x16x32_bf16(Bt[n][k], At[m][k], acc[ai][bj][m][n], 0, 0, 0); __builtin_amdgcn_s_setprio(0); } while (0)
; #define PG8_WAIT_V(n) asm volatile("s_waitcnt vmcnt(" #n ")" ::: "memory")
; #define PG8_WAIT_L(n) asm volatile("s_waitcnt lgkmcnt(" #n ")" ::: "memory")
; #define PG8_BAR __builtin_amdgcn_s_barrier()
; #define PG8_SCHED __builtin_amdgcn_sched_barrier(0)
; template <class Epi, class Sched, bool ALIGN_EPI = false, bool SP2 = false>
; __device__ __forceinline__ void gemm_phase(LAS unsigned char* lds, const Gemm g, const Sched& S, const Epi& E) {
;     ...
;         for (int t = 0; t < nt; t += 2) {
;             const bool last = (t == nt - 2);
;             const char* a1 = cA + (size_t)(t + 1) * kstep;
;             const char* a2 = last ? nA : cA + (size_t)(t + 2) * kstep; const char* b2 = last ? nB : cB + (size_t)(t + 2) * kstep;
;     ...
;             PG8_LDB(B0, 1, 0); PG8_LDB(B1, 1, 1); PG8_SCHED; PG8_LDA(At, 1, 0); PG8_STAGE(PG8_SA(0, 1), a2 + hstep, voffA);
;             PG8_WAIT_V(8); PG8_WAIT_L(0); PG8_BAR; PG8_MMA(0, 0, At, B0); PG8_MMA(0, 1, At, B1); PG8_BAR; PG8_SCHED;
;             PG8_LDA(At, 1, 1); PG8_STAGE(PG8_SB(1, 0), b3, voffB); PG8_STAGE(PG8_SB(1, 1), b3 + hstep, voffB); PG8_STAGE(PG8_SA(1, 0), a3, voffA);
;             PG8_WAIT_V(8); PG8_WAIT_L(0); PG8_BAR; PG8_MMA(1, 0, At, B0); PG8_MMA(1, 1, At, B1); PG8_BAR; PG8_SCHED;
	s_add_i32 s63, 0, 0x18000
	s_add_i32 s64, 0, 0x1c000
	v_add_u32_e32 v140, s63, v177
	v_add_u32_e32 v172, s64, v177
	ds_read_b128 v[128:131], v140
	ds_read_b128 v[132:135], v140 offset:1024
	ds_read_b128 v[136:139], v140 offset:2048
	ds_read_b128 v[140:143], v140 offset:3072
	ds_read_b128 v[144:147], v172
	ds_read_b128 v[148:151], v172 offset:1024
	ds_read_b128 v[168:171], v172 offset:2048
	ds_read_b128 v[172:175], v172 offset:3072
	s_add_u32 s36, s42, 0x160000
	s_addc_u32 s37, s43, 0
	s_mov_b32 m0, s45
	ds_read_b128 v[178:181], v193 offset:32768
	ds_read_b128 v[182:185], v193 offset:33792
	ds_read_b128 v[194:197], v193 offset:34816
	ds_read_b128 v[198:201], v193 offset:35840
	ds_read_b128 v[202:205], v193 offset:36864
	ds_read_b128 v[206:209], v193 offset:37888
	ds_read_b128 v[210:213], v193 offset:38912
	ds_read_b128 v[214:217], v193 offset:39936
	global_load_lds_dwordx4 v152, s[36:37]
	s_mov_b32 m0, s46
	s_nop 0
	global_load_lds_dwordx4 v156, s[36:37]
	s_waitcnt vmcnt(8)
	s_waitcnt lgkmcnt(0)
	s_setprio 1
	s_barrier
	v_mfma_f32_16x16x32_bf16 v[124:127], v[128:131], v[178:181], v[124:127]
	v_mfma_f32_16x16x32_bf16 v[120:123], v[136:139], v[178:181], v[120:123]
	v_mfma_f32_16x16x32_bf16 v[108:111], v[128:131], v[194:197], v[108:111]
	v_mfma_f32_16x16x32_bf16 v[104:107], v[136:139], v[194:197], v[104:107]
	v_mfma_f32_16x16x32_bf16 v[92:95], v[128:131], v[202:205], v[92:95]
	v_mfma_f32_16x16x32_bf16 v[88:91], v[136:139], v[202:205], v[88:91]
	v_mfma_f32_16x16x32_bf16 v[76:79], v[128:131], v[210:213], v[76:79]
	v_mfma_f32_16x16x32_bf16 v[72:75], v[136:139], v[210:213], v[72:75]
	v_mfma_f32_16x16x32_bf16 v[124:127], v[132:135], v[182:185], v[124:127]
	v_mfma_f32_16x16x32_bf16 v[120:123], v[140:143], v[182:185], v[120:123]
	v_mfma_f32_16x16x32_bf16 v[108:111], v[132:135], v[198:201], v[108:111]
	v_mfma_f32_16x16x32_bf16 v[104:107], v[140:143], v[198:201], v[104:107]
	v_mfma_f32_16x16x32_bf16 v[92:95], v[132:135], v[206:209], v[92:95]
	v_mfma_f32_16x16x32_bf16 v[88:91], v[140:143], v[206:209], v[88:91]
	v_mfma_f32_16x16x32_bf16 v[76:79], v[132:135], v[214:217], v[76:79]
	v_mfma_f32_16x16x32_bf16 v[72:75], v[140:143], v[214:217], v[72:75]
	v_mfma_f32_16x16x32_bf16 v[116:119], v[144:147], v[178:181], v[116:119]
	v_mfma_f32_16x16x32_bf16 v[112:115], v[168:171], v[178:181], v[112:115]
	v_mfma_f32_16x16x32_bf16 v[100:103], v[144:147], v[194:197], v[100:103]
	v_mfma_f32_16x16x32_bf16 v[96:99], v[168:171], v[194:197], v[96:99]
	v_mfma_f32_16x16x32_bf16 v[84:87], v[144:147], v[202:205], v[84:87]
	v_mfma_f32_16x16x32_bf16 v[80:83], v[168:171], v[202:205], v[80:83]
	v_mfma_f32_16x16x32_bf16 v[68:71], v[144:147], v[210:213], v[68:71]
	v_mfma_f32_16x16x32_bf16 v[64:67], v[168:171], v[210:213], v[64:67]
	v_mfma_f32_16x16x32_bf16 v[116:119], v[148:151], v[182:185], v[116:119]
	v_mfma_f32_16x16x32_bf16 v[112:115], v[172:175], v[182:185], v[112:115]
	v_mfma_f32_16x16x32_bf16 v[100:103], v[148:151], v[198:201], v[100:103]
	v_mfma_f32_16x16x32_bf16 v[96:99], v[172:175], v[198:201], v[96:99]
	v_mfma_f32_16x16x32_bf16 v[84:87], v[148:151], v[206:209], v[84:87]
	v_mfma_f32_16x16x32_bf16 v[80:83], v[172:175], v[206:209], v[80:83]
	v_mfma_f32_16x16x32_bf16 v[68:71], v[148:151], v[214:217], v[68:71]
	v_mfma_f32_16x16x32_bf16 v[64:67], v[172:175], v[214:217], v[64:67]
	s_setprio 0
	s_barrier
	s_add_i32 s36, s63, s15
	s_mov_b32 m0, s36
	ds_read_b128 v[178:181], v193 offset:49152
	ds_read_b128 v[182:185], v193 offset:50176
	ds_read_b128 v[194:197], v193 offset:51200
	ds_read_b128 v[198:201], v193 offset:52224
	ds_read_b128 v[202:205], v193 offset:53248
	ds_read_b128 v[206:209], v193 offset:54272
	ds_read_b128 v[210:213], v193 offset:55296
	ds_read_b128 v[214:217], v193 offset:56320
	global_load_lds_dwordx4 v154, s[98:99]
	s_add_i32 m0, s36, 0x2000
	s_add_u32 s36, s40, 0x160080
	s_addc_u32 s37, s41, 0
	s_add_i32 s40, s64, s15
	global_load_lds_dwordx4 v158, s[98:99]
	s_mov_b32 m0, s40
	s_nop 0
	global_load_lds_dwordx4 v154, s[36:37]
	s_add_i32 m0, s40, 0x2000
	s_nop 0
	global_load_lds_dwordx4 v158, s[36:37]
	s_mov_b32 m0, s48
	s_nop 0
	global_load_lds_dwordx4 v152, s[100:101]
	s_mov_b32 m0, s49
	s_nop 0
	global_load_lds_dwordx4 v156, s[100:101]
	s_waitcnt vmcnt(8)
	s_waitcnt lgkmcnt(0)
	s_setprio 1
	s_barrier
	v_mfma_f32_16x16x32_bf16 v[60:63], v[128:131], v[178:181], v[60:63]
	v_mfma_f32_16x16x32_bf16 v[56:59], v[136:139], v[178:181], v[56:59]
	v_mfma_f32_16x16x32_bf16 v[44:47], v[128:131], v[194:197], v[44:47]
	v_mfma_f32_16x16x32_bf16 v[40:43], v[136:139], v[194:197], v[40:43]
	v_mfma_f32_16x16x32_bf16 v[28:31], v[128:131], v[202:205], v[28:31]
	v_mfma_f32_16x16x32_bf16 v[24:27], v[136:139], v[202:205], v[24:27]
	v_mfma_f32_16x16x32_bf16 v[12:15], v[128:131], v[210:213], v[12:15]
	v_mfma_f32_16x16x32_bf16 v[8:11], v[136:139], v[210:213], v[8:11]
	v_mfma_f32_16x16x32_bf16 v[60:63], v[132:135], v[182:185], v[60:63]
	v_mfma_f32_16x16x32_bf16 v[56:59], v[140:143], v[182:185], v[56:59]
	v_mfma_f32_16x16x32_bf16 v[44:47], v[132:135], v[198:201], v[44:47]
	v_mfma_f32_16x16x32_bf16 v[40:43], v[140:143], v[198:201], v[40:43]
	v_mfma_f32_16x16x32_bf16 v[28:31], v[132:135], v[206:209], v[28:31]
	v_mfma_f32_16x16x32_bf16 v[24:27], v[140:143], v[206:209], v[24:27]
	v_mfma_f32_16x16x32_bf16 v[12:15], v[132:135], v[214:217], v[12:15]
	v_mfma_f32_16x16x32_bf16 v[8:11], v[140:143], v[214:217], v[8:11]
	v_mfma_f32_16x16x32_bf16 v[52:55], v[144:147], v[178:181], v[52:55]
	v_mfma_f32_16x16x32_bf16 v[48:51], v[168:171], v[178:181], v[48:51]
	v_mfma_f32_16x16x32_bf16 v[36:39], v[144:147], v[194:197], v[36:39]
	v_mfma_f32_16x16x32_bf16 v[32:35], v[168:171], v[194:197], v[32:35]
	v_mfma_f32_16x16x32_bf16 v[20:23], v[144:147], v[202:205], v[20:23]
	v_mfma_f32_16x16x32_bf16 v[16:19], v[168:171], v[202:205], v[16:19]
	v_mfma_f32_16x16x32_bf16 v[4:7], v[144:147], v[210:213], v[4:7]
	v_mfma_f32_16x16x32_bf16 v[0:3], v[168:171], v[210:213], v[0:3]
	v_mfma_f32_16x16x32_bf16 v[52:55], v[148:151], v[182:185], v[52:55]
	v_mfma_f32_16x16x32_bf16 v[48:51], v[172:175], v[182:185], v[48:51]
	v_mfma_f32_16x16x32_bf16 v[36:39], v[148:151], v[198:201], v[36:39]
	v_mfma_f32_16x16x32_bf16 v[32:35], v[172:175], v[198:201], v[32:35]
	v_mfma_f32_16x16x32_bf16 v[20:23], v[148:151], v[206:209], v[20:23]
	v_mfma_f32_16x16x32_bf16 v[16:19], v[172:175], v[206:209], v[16:19]
	v_mfma_f32_16x16x32_bf16 v[4:7], v[148:151], v[214:217], v[4:7]
	v_mfma_f32_16x16x32_bf16 v[0:3], v[172:175], v[214:217], v[0:3]
	s_setprio 0
	s_barrier
	s_add_i32 s62, s62, 2
	s_add_u32 s16, s16, 0x100
	s_addc_u32 s17, s17, 0
	s_cmpk_gt_u32 s62, 0x55
	s_mov_b64 s[36:37], s[38:39]
	s_cbranch_scc0 .LBB0_794
	s_branch .Lsapad3
	s_nop 0
	s_nop 0
	s_nop 0
	s_nop 0
	s_nop 0
	s_nop 0
	s_nop 0
	s_nop 0
	s_nop 0
	s_nop 0
	s_nop 0
	s_nop 0
	s_nop 0
	s_nop 0
	s_nop 0
	s_nop 0
	s_nop 0
	s_nop 0
	s_nop 0
	s_nop 0
	s_nop 0
	s_nop 0
	s_nop 0
	s_nop 0
	s_nop 0
	s_nop 0
	s_nop 0
	s_nop 0
	s_nop 0
	s_nop 0
	s_nop 0
	s_nop 0
	s_nop 0
	s_nop 0
	s_nop 0
	s_nop 0
